# stack: P3 wide-store batched epilogue + ev and eu row-address math 3 VALU->1 (saddr-form gathers)
# speedup vs baseline: 1.0135x; 1.0135x over previous
; #define EU_IDS(t, i0, i1, xq) do { i0 = sel_i[(size_t)(t) * 128 + lane]; i1 = sel_i[(size_t)(t) * 128 + 64 + lane]; \
;                                    xq = *(const uint4*)(h1f8 + (size_t)(t) * 1024 + 128 * cs + 16 * (lane & 7)); } while (0)
; DI void eu_load(const unsigned char* __restrict__ ub8, const int id0, const int id1, const int cs, const int lane, uint4 (&u)[16]) {
; #pragma unroll
;   for (int i = 0; i < 16; ++i) {
;     const int id = __shfl(i < 8 ? id0 : id1, (8 * i + (lane >> 3)) & 63, 64);
;     u[i] = *(const uint4*)(ub8 + (size_t)id * 1024 + 128 * cs + 16 * (lane & 7));
;   }
; }
; DI void eu_compute(const uint4 (&u)[16], const uint4& xq, int* __restrict__ pd, const int lane) {
;   int p[16];
; #pragma unroll
;   for (int i = 0; i < 16; ++i) {
;     int acc = __builtin_amdgcn_sdot4((int)u[i].x, (int)xq.x, 0, false);
;     acc = __builtin_amdgcn_sdot4((int)u[i].y, (int)xq.y, acc, false);
;     acc = __builtin_amdgcn_sdot4((int)u[i].z, (int)xq.z, acc, false);
;     p[i] = __builtin_amdgcn_sdot4((int)u[i].w, (int)xq.w, acc, false);
;   }
; DI void phase_eu(const Params& p, const unsigned my_xcc, const unsigned my_rank) {
;     ...
;   for (int cs = 0; cs < 8; ++cs) {
;     if (!((so.mine >> cs) & 1u)) continue;
;     const int nblk = so.nblk;
;     int* pd = pdot + (size_t)cs * T * 128;
;     if ((int)my_rank >= T / 8) continue;
;     const int K = (T / 8 - (int)my_rank + nblk - 1) / nblk;
;     ...
;     int tA = TOK(0), tB = TOK(1);
;     int a0, a1, b0, b1; uint4 xa, xb;
;     EU_IDS(tA, a0, a1, xa);
;     EU_IDS(tB, b0, b1, xb);
;     uint4 uA[16], uB[16];
;     eu_load(ub8, a0, a1, cs, lane, uA);
;     for (int k = 0; k < K; k += 2) {
;       eu_load(ub8, b0, b1, cs, lane, uB);
;       const int tA2 = TOK(k + 2); int na0, na1; uint4 nxa;
;       EU_IDS(tA2, na0, na1, nxa);
;       eu_compute(uA, xa, pd + (size_t)tA * 128, lane);
;       eu_load(ub8, na0, na1, cs, lane, uA);
.LBB0_456:
	s_waitcnt lgkmcnt(14)
	v_lshrrev_b32_e32 v2, s17, v132
	v_and_b32_e32 v2, 1, v2
	v_cmp_eq_u32_e32 vcc, 0, v2
	s_cbranch_vccnz .LBB0_455
	s_and_b64 vcc, exec, s[12:13]
	s_cbranch_vccnz .LBB0_455
	global_load_dword v3, v[84:85], off
	global_load_dword v5, v[84:85], off offset:256
	s_and_b64 vcc, exec, s[14:15]
	s_waitcnt vmcnt(1)
	ds_bpermute_b32 v2, v134, v3
	ds_bpermute_b32 v4, v134, v3 offset:32
	s_waitcnt lgkmcnt(14)
	ds_bpermute_b32 v46, v134, v3 offset:64
	ds_bpermute_b32 v48, v134, v3 offset:96
	s_waitcnt lgkmcnt(14)
	ds_bpermute_b32 v50, v134, v3 offset:128
	ds_bpermute_b32 v38, v134, v3 offset:160
	s_waitcnt lgkmcnt(14)
	ds_bpermute_b32 v40, v134, v3 offset:192
	ds_bpermute_b32 v30, v134, v3 offset:224
	s_waitcnt vmcnt(0) lgkmcnt(14)
	ds_bpermute_b32 v32, v134, v5
	ds_bpermute_b32 v22, v134, v5 offset:32
	s_waitcnt lgkmcnt(14)
	ds_bpermute_b32 v24, v134, v5 offset:64
	ds_bpermute_b32 v14, v134, v5 offset:96
	s_waitcnt lgkmcnt(14)
	ds_bpermute_b32 v16, v134, v5 offset:128
	ds_bpermute_b32 v6, v134, v5 offset:160
	s_waitcnt lgkmcnt(14)
	ds_bpermute_b32 v8, v134, v5 offset:192
	ds_bpermute_b32 v10, v134, v5 offset:224
	s_cbranch_vccnz .LBB0_455
	s_lshl_b32 s22, s17, 7
	v_and_b32_e32 v211, 7, v0
	v_lshl_add_u32 v211, v211, 4, s22
	s_add_u32 s100, s72, 0x4c00000
	s_addc_u32 s101, s73, 0
	s_waitcnt lgkmcnt(1)
	v_lshl_add_u64 v[92:93], v[78:79], 0, s[22:23]
	s_waitcnt lgkmcnt(0)
	v_lshl_add_u32 v18, v8, 10, v211
	v_lshl_add_u32 v20, v6, 10, v211
	v_lshl_add_u32 v26, v16, 10, v211
	v_lshl_add_u32 v28, v14, 10, v211
	v_lshl_add_u32 v34, v24, 10, v211
	v_lshl_add_u32 v36, v22, 10, v211
	v_lshl_add_u32 v42, v32, 10, v211
	v_lshl_add_u32 v44, v30, 10, v211
	v_lshl_add_u32 v52, v40, 10, v211
	v_lshl_add_u32 v54, v38, 10, v211
	v_lshl_add_u32 v58, v50, 10, v211
	v_lshl_add_u32 v46, v46, 10, v211
	v_lshl_add_u32 v94, v10, 10, v211
	global_load_dwordx4 v[6:9], v18, s[100:101]
	global_load_dwordx4 v[10:13], v20, s[100:101]
	global_load_dwordx4 v[14:17], v26, s[100:101]
	s_nop 0
	global_load_dwordx4 v[18:21], v28, s[100:101]
	global_load_dwordx4 v[22:25], v34, s[100:101]
	s_nop 0
	global_load_dwordx4 v[26:29], v36, s[100:101]
	global_load_dwordx4 v[30:33], v42, s[100:101]
	s_nop 0
	global_load_dwordx4 v[34:37], v44, s[100:101]
	global_load_dwordx4 v[38:41], v52, s[100:101]
	s_nop 0
	global_load_dwordx4 v[42:45], v54, s[100:101]
	v_lshl_add_u32 v48, v48, 10, v211
	global_load_dwordx4 v[50:53], v58, s[100:101]
	global_load_dwordx4 v[54:57], v48, s[100:101]
	v_lshl_add_u32 v4, v4, 10, v211
	global_load_dwordx4 v[58:61], v46, s[100:101]
	global_load_dwordx4 v[62:65], v4, s[100:101]
	v_lshl_add_u32 v46, v2, 10, v211
	v_lshl_add_u64 v[48:49], v[86:87], 0, s[22:23]
	global_load_dwordx4 v[66:69], v46, s[100:101]
	global_load_dwordx4 v[2:5], v[48:49], off
	global_load_dwordx4 v[70:73], v94, s[100:101]
	global_load_dword v99, v[88:89], off offset:256
	global_load_dword v101, v[88:89], off
	v_lshl_add_u64 v[46:47], v[90:91], 0, s[22:23]
	global_load_dwordx4 v[46:49], v[46:47], off
	v_cmp_lt_i32_e32 vcc, v142, v143
	s_lshl_b32 s0, s17, 22
	s_mov_b32 s1, s23
	v_cndmask_b32_e32 v96, v133, v142, vcc
	v_cmp_lt_i32_e32 vcc, v144, v143
	v_lshlrev_b32_e32 v146, 2, v96
	v_lshl_add_u64 v[94:95], v[80:81], 0, s[22:23]
	v_cndmask_b32_e32 v96, v133, v144, vcc
	v_cmp_lt_i32_e32 vcc, v145, v143
	v_lshlrev_b32_e32 v147, 2, v96
	s_mov_b32 s19, 3
	v_cndmask_b32_e32 v96, v133, v145, vcc
	v_lshlrev_b32_e32 v148, 2, v96
	v_lshl_add_u64 v[96:97], s[0:1], 2, v[82:83]
	s_mov_b32 s26, s16
	s_mov_b32 s24, s18
.LBB0_460:
	s_waitcnt vmcnt(1)
	ds_bpermute_b32 v98, v134, v101
	s_add_i32 s0, s19, -1
	ds_bpermute_b32 v100, v135, v101
	ds_bpermute_b32 v102, v136, v101
	ds_bpermute_b32 v104, v137, v101
	ds_bpermute_b32 v106, v138, v101
	ds_bpermute_b32 v108, v139, v101
	ds_bpermute_b32 v110, v140, v101
	ds_bpermute_b32 v112, v141, v101
	ds_bpermute_b32 v114, v134, v99
	ds_bpermute_b32 v116, v135, v99
	ds_bpermute_b32 v118, v136, v99
	ds_bpermute_b32 v120, v137, v99
	ds_bpermute_b32 v122, v138, v99
	ds_bpermute_b32 v124, v139, v99
	ds_bpermute_b32 v126, v140, v99
	ds_bpermute_b32 v128, v141, v99
	s_min_i32 s22, s0, s29
	v_mov_b32_e32 v163, 0
	s_min_i32 s1, s19, s29
	s_mul_i32 s22, s22, s5
	v_mov_b32_e32 v149, 0
	v_mov_b32_e32 v150, 0
	v_mov_b32_e32 v151, 0
	v_mov_b32_e32 v152, 0
	v_mov_b32_e32 v153, 0
	v_mov_b32_e32 v154, 0
	v_mov_b32_e32 v155, 0
	v_mov_b32_e32 v156, 0
	v_mov_b32_e32 v157, 0
	v_mov_b32_e32 v158, 0
	v_mov_b32_e32 v159, 0
	v_mov_b32_e32 v160, 0
	v_mov_b32_e32 v161, 0
	v_mov_b32_e32 v162, 0
	v_mov_b32_e32 v164, 0
	s_waitcnt vmcnt(0)
	v_dot4c_i32_i8_e32 v163, v6, v46
	s_mul_i32 s1, s1, s5
	s_add_i32 s22, s22, s33
	s_ashr_i32 s27, s26, 31
	v_dot4c_i32_i8_e32 v149, v66, v46
	v_dot4c_i32_i8_e32 v150, v62, v46
	v_dot4c_i32_i8_e32 v151, v58, v46
	v_dot4c_i32_i8_e32 v152, v54, v46
	v_dot4c_i32_i8_e32 v153, v50, v46
	v_dot4c_i32_i8_e32 v154, v42, v46
	v_dot4c_i32_i8_e32 v155, v38, v46
	v_dot4c_i32_i8_e32 v156, v34, v46
	v_dot4c_i32_i8_e32 v157, v30, v46
	v_dot4c_i32_i8_e32 v158, v26, v46
	v_dot4c_i32_i8_e32 v159, v22, v46
	v_dot4c_i32_i8_e32 v160, v18, v46
	v_dot4c_i32_i8_e32 v161, v14, v46
	v_dot4c_i32_i8_e32 v162, v10, v46
	v_dot4c_i32_i8_e32 v164, v70, v46
	v_dot4c_i32_i8_e32 v163, v7, v47
	s_add_i32 s1, s1, s33
	s_lshl_b32 s22, s22, 3
	s_lshl_b64 s[26:27], s[26:27], 9
	v_dot4c_i32_i8_e32 v149, v67, v47
	v_dot4c_i32_i8_e32 v150, v63, v47
	v_dot4c_i32_i8_e32 v151, v59, v47
	v_dot4c_i32_i8_e32 v152, v55, v47
	v_dot4c_i32_i8_e32 v153, v51, v47
	v_dot4c_i32_i8_e32 v154, v43, v47
	v_dot4c_i32_i8_e32 v155, v39, v47
	v_dot4c_i32_i8_e32 v156, v35, v47
	v_dot4c_i32_i8_e32 v157, v31, v47
	v_dot4c_i32_i8_e32 v158, v27, v47
	v_dot4c_i32_i8_e32 v159, v23, v47
	v_dot4c_i32_i8_e32 v160, v19, v47
	v_dot4c_i32_i8_e32 v161, v15, v47
	v_dot4c_i32_i8_e32 v162, v11, v47
	v_dot4c_i32_i8_e32 v164, v71, v47
	v_dot4c_i32_i8_e32 v163, v8, v48
	s_lshl_b32 s1, s1, 3
	s_waitcnt lgkmcnt(14)
; #define EU_IDS(t, i0, i1, xq) do { i0 = sel_i[(size_t)(t) * 128 + lane]; i1 = sel_i[(size_t)(t) * 128 + 64 + lane]; \
;                                    xq = *(const uint4*)(h1f8 + (size_t)(t) * 1024 + 128 * cs + 16 * (lane & 7)); } while (0)
; DI void eu_compute(const uint4 (&u)[16], const uint4& xq, int* __restrict__ pd, const int lane) {
;   int p[16];
; #pragma unroll
;   for (int i = 0; i < 16; ++i) {
;     int acc = __builtin_amdgcn_sdot4((int)u[i].x, (int)xq.x, 0, false);
;     acc = __builtin_amdgcn_sdot4((int)u[i].y, (int)xq.y, acc, false);
;     acc = __builtin_amdgcn_sdot4((int)u[i].z, (int)xq.z, acc, false);
;     p[i] = __builtin_amdgcn_sdot4((int)u[i].w, (int)xq.w, acc, false);
;   }
;   int q8[8], q4[4], q2[2];
;   const bool b2 = lane & 4, b1 = lane & 2, b0 = lane & 1;
; #pragma unroll
;   for (int j = 0; j < 8; ++j) { const int keep = b2 ? p[8 + j] : p[j], send = b2 ? p[j] : p[8 + j]; q8[j] = keep + __shfl_xor(send, 4, 64); }
; #pragma unroll
;   for (int j = 0; j < 4; ++j) { const int keep = b1 ? q8[4 + j] : q8[j], send = b1 ? q8[j] : q8[4 + j]; q4[j] = keep + __shfl_xor(send, 2, 64); }
; #pragma unroll
;   for (int j = 0; j < 2; ++j) { const int keep = b0 ? q4[2 + j] : q4[j], send = b0 ? q4[j] : q4[2 + j]; q2[j] = keep + __shfl_xor(send, 1, 64); }
;   const int slot0 = 16 * (lane & 7) + (lane >> 3);
;   pd[slot0] = q2[0];
;   pd[slot0 + 8] = q2[1];
; }
; DI void phase_eu(const Params& p, const unsigned my_xcc, const unsigned my_rank) {
;     ...
;       eu_load(ub8, b0, b1, cs, lane, uB);
;       const int tA2 = TOK(k + 2); int na0, na1; uint4 nxa;
;       EU_IDS(tA2, na0, na1, nxa);
	s_add_i32 s30, s22, s3
	s_ashr_i32 s25, s24, 31
	v_lshl_add_u64 v[6:7], v[96:97], 0, s[26:27]
	v_dot4c_i32_i8_e32 v149, v68, v48
	v_dot4c_i32_i8_e32 v150, v64, v48
	v_dot4c_i32_i8_e32 v151, v60, v48
	v_dot4c_i32_i8_e32 v152, v56, v48
	v_dot4c_i32_i8_e32 v153, v52, v48
	v_dot4c_i32_i8_e32 v154, v44, v48
	v_dot4c_i32_i8_e32 v155, v40, v48
	v_dot4c_i32_i8_e32 v156, v36, v48
	v_dot4c_i32_i8_e32 v157, v32, v48
	v_dot4c_i32_i8_e32 v158, v28, v48
	v_dot4c_i32_i8_e32 v159, v24, v48
	v_dot4c_i32_i8_e32 v160, v20, v48
	v_dot4c_i32_i8_e32 v161, v16, v48
	v_dot4c_i32_i8_e32 v162, v12, v48
	v_dot4c_i32_i8_e32 v164, v72, v48
	v_dot4c_i32_i8_e32 v163, v9, v49
	s_add_i32 s26, s1, s3
	s_waitcnt lgkmcnt(13)
	s_waitcnt lgkmcnt(12)
	s_waitcnt lgkmcnt(11)
	s_waitcnt lgkmcnt(10)
	s_waitcnt lgkmcnt(9)
	s_waitcnt lgkmcnt(8)
	s_waitcnt lgkmcnt(7)
	s_waitcnt lgkmcnt(6)
	s_waitcnt lgkmcnt(5)
	s_waitcnt lgkmcnt(4)
	s_waitcnt lgkmcnt(3)
	s_waitcnt lgkmcnt(2)
	s_waitcnt lgkmcnt(1)
	s_waitcnt lgkmcnt(0)
	s_ashr_i32 s31, s30, 31
	s_lshl_b64 s[24:25], s[24:25], 9
	v_dot4c_i32_i8_e32 v149, v69, v49
	v_dot4c_i32_i8_e32 v150, v65, v49
	v_dot4c_i32_i8_e32 v151, v61, v49
	v_dot4c_i32_i8_e32 v152, v57, v49
	v_dot4c_i32_i8_e32 v153, v53, v49
	v_dot4c_i32_i8_e32 v154, v45, v49
	v_dot4c_i32_i8_e32 v155, v41, v49
	v_dot4c_i32_i8_e32 v156, v37, v49
	v_dot4c_i32_i8_e32 v157, v33, v49
	v_dot4c_i32_i8_e32 v158, v29, v49
	v_dot4c_i32_i8_e32 v159, v25, v49
	v_dot4c_i32_i8_e32 v160, v21, v49
	v_dot4c_i32_i8_e32 v161, v17, v49
	v_dot4c_i32_i8_e32 v162, v13, v49
	v_dot4c_i32_i8_e32 v164, v73, v49
	s_ashr_i32 s27, s26, 31
	v_lshl_add_u32 v8, v98, 10, v211
	s_lshl_b64 s[38:39], s[30:31], 9
	v_lshl_add_u64 v[130:131], v[96:97], 0, s[24:25]
	v_cndmask_b32_e64 v44, v157, v149, s[6:7]
	v_cndmask_b32_e64 v40, v149, v157, s[6:7]
	v_cndmask_b32_e64 v45, v158, v150, s[6:7]
	v_cndmask_b32_e64 v41, v150, v158, s[6:7]
	v_cndmask_b32_e64 v50, v159, v151, s[6:7]
	v_cndmask_b32_e64 v42, v151, v159, s[6:7]
	v_cndmask_b32_e64 v51, v160, v152, s[6:7]
	v_cndmask_b32_e64 v43, v152, v160, s[6:7]
	v_cndmask_b32_e64 v52, v161, v153, s[6:7]
	v_cndmask_b32_e64 v46, v153, v161, s[6:7]
	v_cndmask_b32_e64 v53, v162, v154, s[6:7]
	v_cndmask_b32_e64 v47, v154, v162, s[6:7]
	v_cndmask_b32_e64 v54, v163, v155, s[6:7]
	v_cndmask_b32_e64 v48, v155, v163, s[6:7]
	v_cndmask_b32_e64 v55, v164, v156, s[6:7]
	v_cndmask_b32_e64 v49, v156, v164, s[6:7]
	s_mov_b32 s24, s26
	s_lshl_b64 s[34:35], s[26:27], 9
	s_lshl_b64 s[36:37], s[26:27], 10
	s_mov_b32 s26, s30
	v_lshl_add_u32 v10, v100, 10, v211
	v_lshl_add_u32 v12, v102, 10, v211
	v_lshl_add_u32 v14, v104, 10, v211
	v_lshl_add_u32 v16, v106, 10, v211
	v_lshl_add_u32 v18, v108, 10, v211
	v_lshl_add_u32 v20, v110, 10, v211
	v_lshl_add_u32 v22, v112, 10, v211
	v_lshl_add_u32 v24, v114, 10, v211
	v_lshl_add_u32 v26, v116, 10, v211
	v_lshl_add_u32 v28, v118, 10, v211
	v_lshl_add_u32 v30, v120, 10, v211
	v_lshl_add_u32 v32, v122, 10, v211
	v_lshl_add_u32 v34, v124, 10, v211
	v_lshl_add_u32 v36, v126, 10, v211
	v_lshl_add_u32 v38, v128, 10, v211
	s_lshl_b64 s[30:31], s[30:31], 10
	global_load_dwordx4 v[102:105], v8, s[100:101]
	global_load_dwordx4 v[106:109], v10, s[100:101]
	global_load_dwordx4 v[110:113], v12, s[100:101]
	global_load_dwordx4 v[114:117], v14, s[100:101]
	global_load_dwordx4 v[118:121], v16, s[100:101]
	global_load_dwordx4 v[122:125], v18, s[100:101]
	global_load_dwordx4 v[126:129], v20, s[100:101]
	global_load_dwordx4 v[150:153], v22, s[100:101]
	global_load_dwordx4 v[154:157], v24, s[100:101]
	global_load_dwordx4 v[158:161], v26, s[100:101]
	global_load_dwordx4 v[174:177], v28, s[100:101]
	global_load_dwordx4 v[178:181], v30, s[100:101]
	global_load_dwordx4 v[182:185], v32, s[100:101]
	global_load_dwordx4 v[186:189], v34, s[100:101]
	global_load_dwordx4 v[190:193], v36, s[100:101]
	global_load_dwordx4 v[194:197], v38, s[100:101]
	v_lshl_add_u64 v[8:9], v[76:77], 0, s[38:39]
	ds_bpermute_b32 v60, v146, v46
	ds_bpermute_b32 v61, v146, v47
	ds_bpermute_b32 v62, v146, v48
	ds_bpermute_b32 v63, v146, v49
	v_lshl_add_u64 v[10:11], v[94:95], 0, s[30:31]
	global_load_dword v13, v[8:9], off
	s_nop 0
	global_load_dword v9, v[8:9], off offset:256
	s_nop 0
	global_load_dwordx4 v[46:49], v[10:11], off
	ds_bpermute_b32 v56, v146, v40
	ds_bpermute_b32 v57, v146, v41
	ds_bpermute_b32 v58, v146, v42
	ds_bpermute_b32 v59, v146, v43
	s_waitcnt lgkmcnt(7)
	v_add_u32_e32 v14, v60, v52
	s_waitcnt lgkmcnt(3)
	v_add_u32_e32 v8, v56, v44
	s_waitcnt lgkmcnt(2)
	v_add_u32_e32 v10, v57, v45
	s_waitcnt lgkmcnt(1)
	v_add_u32_e32 v11, v58, v50
	s_waitcnt lgkmcnt(0)
	v_add_u32_e32 v12, v59, v51
	v_add_u32_e32 v15, v61, v53
	v_add_u32_e32 v16, v62, v54
	v_add_u32_e32 v17, v63, v55
	v_cndmask_b32_e64 v18, v14, v8, s[8:9]
	v_cndmask_b32_e64 v8, v8, v14, s[8:9]
	v_cndmask_b32_e64 v14, v15, v10, s[8:9]
	v_cndmask_b32_e64 v10, v10, v15, s[8:9]
	v_cndmask_b32_e64 v15, v16, v11, s[8:9]
	v_cndmask_b32_e64 v11, v11, v16, s[8:9]
	v_cndmask_b32_e64 v16, v17, v12, s[8:9]
	v_cndmask_b32_e64 v12, v12, v17, s[8:9]
	ds_bpermute_b32 v8, v147, v8
	ds_bpermute_b32 v10, v147, v10
	ds_bpermute_b32 v11, v147, v11
	ds_bpermute_b32 v12, v147, v12
	v_mov_b32_e32 v165, 0
	s_waitcnt lgkmcnt(3)
	v_add_u32_e32 v8, v8, v18
	s_waitcnt lgkmcnt(2)
	v_add_u32_e32 v10, v10, v14
	s_waitcnt lgkmcnt(1)
	v_add_u32_e32 v11, v11, v15
	s_waitcnt lgkmcnt(0)
; #define EU_IDS(t, i0, i1, xq) do { i0 = sel_i[(size_t)(t) * 128 + lane]; i1 = sel_i[(size_t)(t) * 128 + 64 + lane]; \
;                                    xq = *(const uint4*)(h1f8 + (size_t)(t) * 1024 + 128 * cs + 16 * (lane & 7)); } while (0)
; DI void eu_compute(const uint4 (&u)[16], const uint4& xq, int* __restrict__ pd, const int lane) {
;   int p[16];
; #pragma unroll
;   for (int i = 0; i < 16; ++i) {
;     int acc = __builtin_amdgcn_sdot4((int)u[i].x, (int)xq.x, 0, false);
;     acc = __builtin_amdgcn_sdot4((int)u[i].y, (int)xq.y, acc, false);
;     acc = __builtin_amdgcn_sdot4((int)u[i].z, (int)xq.z, acc, false);
;     p[i] = __builtin_amdgcn_sdot4((int)u[i].w, (int)xq.w, acc, false);
;   }
;   int q8[8], q4[4], q2[2];
;   const bool b2 = lane & 4, b1 = lane & 2, b0 = lane & 1;
; #pragma unroll
;   for (int j = 0; j < 8; ++j) { const int keep = b2 ? p[8 + j] : p[j], send = b2 ? p[j] : p[8 + j]; q8[j] = keep + __shfl_xor(send, 4, 64); }
; #pragma unroll
;   for (int j = 0; j < 4; ++j) { const int keep = b1 ? q8[4 + j] : q8[j], send = b1 ? q8[j] : q8[4 + j]; q4[j] = keep + __shfl_xor(send, 2, 64); }
; #pragma unroll
;   for (int j = 0; j < 2; ++j) { const int keep = b0 ? q4[2 + j] : q4[j], send = b0 ? q4[j] : q4[2 + j]; q2[j] = keep + __shfl_xor(send, 1, 64); }
;   const int slot0 = 16 * (lane & 7) + (lane >> 3);
;   pd[slot0] = q2[0];
;   pd[slot0 + 8] = q2[1];
; }
; DI void phase_eu(const Params& p, const unsigned my_xcc, const unsigned my_rank) {
;     ...
;       const int tB2 = TOK(k + 3); int nb0, nb1; uint4 nxb;
;       EU_IDS(tB2, nb0, nb1, nxb);
;       eu_compute(uB, xb, pd + (size_t)tB * 128, lane);
	v_add_u32_e32 v12, v12, v16
	v_cndmask_b32_e64 v14, v11, v8, s[10:11]
	v_cndmask_b32_e64 v8, v8, v11, s[10:11]
	v_cndmask_b32_e64 v11, v12, v10, s[10:11]
	v_cndmask_b32_e64 v10, v10, v12, s[10:11]
	ds_bpermute_b32 v8, v148, v8
	ds_bpermute_b32 v10, v148, v10
	v_mov_b32_e32 v166, 0
	v_mov_b32_e32 v167, 0
	v_mov_b32_e32 v168, 0
	v_mov_b32_e32 v169, 0
	v_mov_b32_e32 v170, 0
	v_mov_b32_e32 v171, 0
	v_mov_b32_e32 v172, 0
	v_mov_b32_e32 v173, 0
	v_mov_b32_e32 v198, 0
	v_mov_b32_e32 v199, 0
	v_mov_b32_e32 v206, 0
	v_mov_b32_e32 v207, 0
	v_mov_b32_e32 v208, 0
	v_mov_b32_e32 v209, 0
	v_mov_b32_e32 v210, 0
	s_waitcnt lgkmcnt(1)
	v_add_u32_e32 v8, v8, v14
	s_waitcnt lgkmcnt(0)
	v_add_u32_e32 v10, v10, v11
	global_store_dword v[6:7], v8, off
	global_store_dword v[6:7], v10, off offset:32
	v_lshl_add_u64 v[40:41], v[76:77], 0, s[34:35]
	v_lshl_add_u64 v[42:43], v[94:95], 0, s[36:37]
	global_load_dword v101, v[40:41], off
	global_load_dword v99, v[40:41], off offset:256
	global_load_dwordx4 v[202:205], v[42:43], off
	s_add_i32 s19, s19, 2
	s_waitcnt vmcnt(23)
	v_dot4c_i32_i8_e32 v165, v102, v2
	s_waitcnt vmcnt(22)
	v_dot4c_i32_i8_e32 v166, v106, v2
	s_waitcnt vmcnt(21)
	v_dot4c_i32_i8_e32 v167, v110, v2
	s_waitcnt vmcnt(20)
	v_dot4c_i32_i8_e32 v168, v114, v2
	s_waitcnt vmcnt(19)
	v_dot4c_i32_i8_e32 v169, v118, v2
	s_waitcnt vmcnt(18)
	v_dot4c_i32_i8_e32 v170, v122, v2
	s_waitcnt vmcnt(17)
	v_dot4c_i32_i8_e32 v171, v126, v2
	s_waitcnt vmcnt(16)
	v_dot4c_i32_i8_e32 v172, v150, v2
	s_waitcnt vmcnt(15)
	v_dot4c_i32_i8_e32 v173, v154, v2
	s_waitcnt vmcnt(14)
	v_dot4c_i32_i8_e32 v198, v158, v2
	s_waitcnt vmcnt(13)
	v_dot4c_i32_i8_e32 v199, v174, v2
	s_waitcnt vmcnt(12)
	v_dot4c_i32_i8_e32 v206, v178, v2
	s_waitcnt vmcnt(11)
	v_dot4c_i32_i8_e32 v207, v182, v2
	s_waitcnt vmcnt(10)
	v_dot4c_i32_i8_e32 v208, v186, v2
	s_waitcnt vmcnt(9)
	v_dot4c_i32_i8_e32 v209, v190, v2
	s_waitcnt vmcnt(8)
	v_dot4c_i32_i8_e32 v210, v194, v2
	v_dot4c_i32_i8_e32 v165, v103, v3
	v_dot4c_i32_i8_e32 v166, v107, v3
	v_dot4c_i32_i8_e32 v167, v111, v3
	v_dot4c_i32_i8_e32 v168, v115, v3
	s_waitcnt vmcnt(7)
	ds_bpermute_b32 v2, v134, v13
	ds_bpermute_b32 v6, v135, v13
	ds_bpermute_b32 v8, v136, v13
	ds_bpermute_b32 v10, v137, v13
	ds_bpermute_b32 v12, v138, v13
	ds_bpermute_b32 v14, v139, v13
	ds_bpermute_b32 v16, v140, v13
	ds_bpermute_b32 v18, v141, v13
	s_waitcnt vmcnt(6)
	ds_bpermute_b32 v20, v134, v9
	ds_bpermute_b32 v22, v135, v9
	ds_bpermute_b32 v24, v136, v9
	ds_bpermute_b32 v26, v137, v9
	ds_bpermute_b32 v28, v138, v9
	ds_bpermute_b32 v30, v139, v9
	ds_bpermute_b32 v32, v140, v9
	ds_bpermute_b32 v34, v141, v9
	v_dot4c_i32_i8_e32 v169, v119, v3
	v_dot4c_i32_i8_e32 v170, v123, v3
	v_dot4c_i32_i8_e32 v171, v127, v3
	v_dot4c_i32_i8_e32 v172, v151, v3
	v_dot4c_i32_i8_e32 v173, v155, v3
	v_dot4c_i32_i8_e32 v198, v159, v3
	v_dot4c_i32_i8_e32 v199, v175, v3
	v_dot4c_i32_i8_e32 v206, v179, v3
	v_dot4c_i32_i8_e32 v207, v183, v3
	v_dot4c_i32_i8_e32 v208, v187, v3
	v_dot4c_i32_i8_e32 v209, v191, v3
	v_dot4c_i32_i8_e32 v210, v195, v3
	s_waitcnt lgkmcnt(14)
	s_waitcnt lgkmcnt(13)
	s_waitcnt lgkmcnt(12)
	s_waitcnt lgkmcnt(11)
	s_waitcnt lgkmcnt(10)
	s_waitcnt lgkmcnt(9)
	s_waitcnt lgkmcnt(8)
	s_waitcnt lgkmcnt(7)
	s_waitcnt lgkmcnt(6)
	s_waitcnt lgkmcnt(5)
	s_waitcnt lgkmcnt(4)
	s_waitcnt lgkmcnt(3)
	s_waitcnt lgkmcnt(2)
	s_waitcnt lgkmcnt(1)
	s_waitcnt lgkmcnt(0)
; #define EU_IDS(t, i0, i1, xq) do { i0 = sel_i[(size_t)(t) * 128 + lane]; i1 = sel_i[(size_t)(t) * 128 + 64 + lane]; \
;                                    xq = *(const uint4*)(h1f8 + (size_t)(t) * 1024 + 128 * cs + 16 * (lane & 7)); } while (0)
; DI void eu_load(const unsigned char* __restrict__ ub8, const int id0, const int id1, const int cs, const int lane, uint4 (&u)[16]) {
; #pragma unroll
;   for (int i = 0; i < 16; ++i) {
;     const int id = __shfl(i < 8 ? id0 : id1, (8 * i + (lane >> 3)) & 63, 64);
;     u[i] = *(const uint4*)(ub8 + (size_t)id * 1024 + 128 * cs + 16 * (lane & 7));
;   }
; }
; DI void eu_compute(const uint4 (&u)[16], const uint4& xq, int* __restrict__ pd, const int lane) {
;   int p[16];
; #pragma unroll
;   for (int i = 0; i < 16; ++i) {
;     int acc = __builtin_amdgcn_sdot4((int)u[i].x, (int)xq.x, 0, false);
;     acc = __builtin_amdgcn_sdot4((int)u[i].y, (int)xq.y, acc, false);
;     acc = __builtin_amdgcn_sdot4((int)u[i].z, (int)xq.z, acc, false);
;     p[i] = __builtin_amdgcn_sdot4((int)u[i].w, (int)xq.w, acc, false);
;   }
;   int q8[8], q4[4], q2[2];
;   const bool b2 = lane & 4, b1 = lane & 2, b0 = lane & 1;
; #pragma unroll
;   for (int j = 0; j < 8; ++j) { const int keep = b2 ? p[8 + j] : p[j], send = b2 ? p[j] : p[8 + j]; q8[j] = keep + __shfl_xor(send, 4, 64); }
; #pragma unroll
;   for (int j = 0; j < 4; ++j) { const int keep = b1 ? q8[4 + j] : q8[j], send = b1 ? q8[j] : q8[4 + j]; q4[j] = keep + __shfl_xor(send, 2, 64); }
; #pragma unroll
;   for (int j = 0; j < 2; ++j) { const int keep = b0 ? q4[2 + j] : q4[j], send = b0 ? q4[j] : q4[2 + j]; q2[j] = keep + __shfl_xor(send, 1, 64); }
;   const int slot0 = 16 * (lane & 7) + (lane >> 3);
;   pd[slot0] = q2[0];
;   pd[slot0 + 8] = q2[1];
; }
; DI void phase_eu(const Params& p, const unsigned my_xcc, const unsigned my_rank) {
;     ...
;       eu_load(ub8, na0, na1, cs, lane, uA);
;       const int tB2 = TOK(k + 3); int nb0, nb1; uint4 nxb;
;       EU_IDS(tB2, nb0, nb1, nxb);
;       eu_compute(uB, xb, pd + (size_t)tB * 128, lane);
;       tA = tA2; a0 = na0; a1 = na1; xa = nxa; tB = tB2; b0 = nb0; b1 = nb1; xb = nxb;
;     }
	v_lshl_add_u32 v2, v2, 10, v211
	v_lshl_add_u32 v6, v6, 10, v211
	v_lshl_add_u32 v8, v8, 10, v211
	v_lshl_add_u32 v10, v10, 10, v211
	v_lshl_add_u32 v12, v12, 10, v211
	v_lshl_add_u32 v14, v14, 10, v211
	v_lshl_add_u32 v16, v16, 10, v211
	v_lshl_add_u32 v18, v18, 10, v211
	v_lshl_add_u32 v20, v20, 10, v211
	v_lshl_add_u32 v22, v22, 10, v211
	v_lshl_add_u32 v24, v24, 10, v211
	v_lshl_add_u32 v70, v26, 10, v211
	v_lshl_add_u32 v72, v28, 10, v211
	v_lshl_add_u32 v102, v30, 10, v211
	v_lshl_add_u32 v106, v32, 10, v211
	v_lshl_add_u32 v110, v34, 10, v211
	global_load_dwordx4 v[66:69], v2, s[100:101]
	global_load_dwordx4 v[62:65], v6, s[100:101]
	global_load_dwordx4 v[58:61], v8, s[100:101]
	global_load_dwordx4 v[54:57], v10, s[100:101]
	global_load_dwordx4 v[50:53], v12, s[100:101]
	global_load_dwordx4 v[42:45], v14, s[100:101]
	global_load_dwordx4 v[38:41], v16, s[100:101]
	global_load_dwordx4 v[34:37], v18, s[100:101]
	global_load_dwordx4 v[30:33], v20, s[100:101]
	global_load_dwordx4 v[26:29], v22, s[100:101]
	s_nop 0
	global_load_dwordx4 v[22:25], v24, s[100:101]
	s_nop 0
	global_load_dwordx4 v[18:21], v70, s[100:101]
	global_load_dwordx4 v[14:17], v72, s[100:101]
	global_load_dwordx4 v[10:13], v102, s[100:101]
	global_load_dwordx4 v[6:9], v106, s[100:101]
	s_nop 0
	global_load_dwordx4 v[70:73], v110, s[100:101]
	v_dot4c_i32_i8_e32 v165, v104, v4
	v_dot4c_i32_i8_e32 v166, v108, v4
	v_dot4c_i32_i8_e32 v167, v112, v4
	v_dot4c_i32_i8_e32 v168, v116, v4
	v_dot4c_i32_i8_e32 v169, v120, v4
	v_dot4c_i32_i8_e32 v170, v124, v4
	v_dot4c_i32_i8_e32 v171, v128, v4
	v_dot4c_i32_i8_e32 v173, v156, v4
	v_dot4c_i32_i8_e32 v198, v160, v4
	v_dot4c_i32_i8_e32 v199, v176, v4
	v_dot4c_i32_i8_e32 v206, v180, v4
	v_dot4c_i32_i8_e32 v207, v184, v4
	v_dot4c_i32_i8_e32 v208, v188, v4
	v_dot4c_i32_i8_e32 v209, v192, v4
	v_dot4c_i32_i8_e32 v172, v152, v4
	v_dot4c_i32_i8_e32 v210, v196, v4
	v_dot4c_i32_i8_e32 v165, v105, v5
	v_dot4c_i32_i8_e32 v166, v109, v5
	v_dot4c_i32_i8_e32 v167, v113, v5
	v_dot4c_i32_i8_e32 v168, v117, v5
	v_dot4c_i32_i8_e32 v169, v121, v5
	v_dot4c_i32_i8_e32 v170, v125, v5
	v_dot4c_i32_i8_e32 v171, v129, v5
	v_dot4c_i32_i8_e32 v173, v157, v5
	v_dot4c_i32_i8_e32 v198, v161, v5
	v_dot4c_i32_i8_e32 v199, v177, v5
	v_dot4c_i32_i8_e32 v206, v181, v5
	v_dot4c_i32_i8_e32 v207, v185, v5
	v_dot4c_i32_i8_e32 v208, v189, v5
	v_dot4c_i32_i8_e32 v209, v193, v5
	v_dot4c_i32_i8_e32 v172, v153, v5
	v_dot4c_i32_i8_e32 v210, v197, v5
	v_cndmask_b32_e64 v3, v165, v173, s[6:7]
	v_cndmask_b32_e64 v5, v166, v198, s[6:7]
	v_cndmask_b32_e64 v100, v167, v199, s[6:7]
	v_cndmask_b32_e64 v103, v168, v206, s[6:7]
	v_cndmask_b32_e64 v105, v169, v207, s[6:7]
	v_cndmask_b32_e64 v107, v170, v208, s[6:7]
	v_cndmask_b32_e64 v109, v171, v209, s[6:7]
	v_cndmask_b32_e64 v111, v172, v210, s[6:7]
	ds_bpermute_b32 v3, v146, v3
	ds_bpermute_b32 v5, v146, v5
	ds_bpermute_b32 v100, v146, v100
	ds_bpermute_b32 v103, v146, v103
	ds_bpermute_b32 v105, v146, v105
	ds_bpermute_b32 v107, v146, v107
	ds_bpermute_b32 v109, v146, v109
	ds_bpermute_b32 v111, v146, v111
	v_cndmask_b32_e64 v2, v173, v165, s[6:7]
	v_cndmask_b32_e64 v4, v198, v166, s[6:7]
	v_cndmask_b32_e64 v98, v199, v167, s[6:7]
	v_cndmask_b32_e64 v102, v206, v168, s[6:7]
	v_cndmask_b32_e64 v104, v207, v169, s[6:7]
	v_cndmask_b32_e64 v106, v208, v170, s[6:7]
	v_cndmask_b32_e64 v108, v209, v171, s[6:7]
	v_cndmask_b32_e64 v110, v210, v172, s[6:7]
	s_waitcnt lgkmcnt(7)
	v_add_u32_e32 v2, v3, v2
	s_waitcnt lgkmcnt(6)
	v_add_u32_e32 v3, v5, v4
	s_waitcnt lgkmcnt(5)
	v_add_u32_e32 v4, v100, v98
	s_waitcnt lgkmcnt(4)
	v_add_u32_e32 v5, v103, v102
	s_waitcnt lgkmcnt(3)
	v_add_u32_e32 v98, v105, v104
	s_waitcnt lgkmcnt(2)
	v_add_u32_e32 v100, v107, v106
	s_waitcnt lgkmcnt(1)
	v_add_u32_e32 v102, v109, v108
	s_waitcnt lgkmcnt(0)
	v_add_u32_e32 v103, v111, v110
	v_cndmask_b32_e64 v104, v98, v2, s[8:9]
	v_cndmask_b32_e64 v2, v2, v98, s[8:9]
	v_cndmask_b32_e64 v98, v100, v3, s[8:9]
	v_cndmask_b32_e64 v3, v3, v100, s[8:9]
	v_cndmask_b32_e64 v100, v102, v4, s[8:9]
	v_cndmask_b32_e64 v4, v4, v102, s[8:9]
	v_cndmask_b32_e64 v102, v103, v5, s[8:9]
	v_cndmask_b32_e64 v5, v5, v103, s[8:9]
	ds_bpermute_b32 v2, v147, v2
	ds_bpermute_b32 v4, v147, v4
	ds_bpermute_b32 v3, v147, v3
	ds_bpermute_b32 v5, v147, v5
	s_cmp_lt_i32 s0, s28
	s_waitcnt lgkmcnt(3)
	v_add_u32_e32 v2, v2, v104
	s_waitcnt lgkmcnt(2)
	v_add_u32_e32 v4, v4, v100
	s_waitcnt lgkmcnt(1)
	v_add_u32_e32 v3, v3, v98
	s_waitcnt lgkmcnt(0)
	v_add_u32_e32 v5, v5, v102
	v_cndmask_b32_e64 v98, v4, v2, s[10:11]
	v_cndmask_b32_e64 v2, v2, v4, s[10:11]
	v_cndmask_b32_e64 v4, v3, v5, s[10:11]
	ds_bpermute_b32 v100, v148, v2
	ds_bpermute_b32 v102, v148, v4
	v_cndmask_b32_e64 v103, v5, v3, s[10:11]
	s_waitcnt vmcnt(16)
	v_mov_b64_e32 v[2:3], v[202:203]
	v_mov_b64_e32 v[4:5], v[204:205]
	s_waitcnt lgkmcnt(1)
	v_add_u32_e32 v98, v100, v98
	s_waitcnt lgkmcnt(0)
	v_add_u32_e32 v100, v102, v103
	global_store_dword v[130:131], v98, off
	global_store_dword v[130:131], v100, off offset:32
	s_cbranch_scc1 .LBB0_460
	s_branch .LBB0_455

; #define EV_IDS(t, i0, i1, c0, c1) do { i0 = sel_i[(size_t)(t) * 128 + lane]; i1 = sel_i[(size_t)(t) * 128 + 64 + lane]; \
;                                        c0 = cbuf[(size_t)(t) * 128 + lane]; c1 = cbuf[(size_t)(t) * 128 + 64 + lane]; } while (0)
; DI void ev_load(const unsigned char* __restrict__ vb8, const int id0, const int id1, const int cs, const int lane, uint4 (&v)[16]) {
; #pragma unroll
;   for (int i = 0; i < 16; ++i) {
;     const int id = __shfl(i < 8 ? id0 : id1, (8 * i + (lane >> 3)) & 63, 64);
;     v[i] = *(const uint4*)(vb8 + (size_t)id * 1024 + 128 * cs + 16 * (lane & 7));
;   }
; DI void phase_ev(const Params& p, const unsigned my_xcc, const unsigned my_rank) {
;     ...
;   for (int cs = 0; cs < 8; ++cs) {
;     if (!((so.mine >> cs) & 1u)) continue;
;     const int nblk = so.nblk;
;     if ((int)my_rank >= T / 8) continue;
;     const int K = (T / 8 - (int)my_rank + nblk - 1) / nblk;
;     ...
;     int tA = TOK(0), tB = TOK(1);
;     int a0, a1, b0, b1; float ca0, ca1, cb0, cb1;
;     EV_IDS(tA, a0, a1, ca0, ca1);
;     EV_IDS(tB, b0, b1, cb0, cb1);
;     uint4 vA[16], vB[16];
;     ev_load(vb8, a0, a1, cs, lane, vA);
;     for (int k = 0; k < K; k += 2) {
;       ev_load(vb8, b0, b1, cs, lane, vB);
;       const int tA2 = TOK(k + 2); int na0, na1; float nca0, nca1;
;       EV_IDS(tA2, na0, na1, nca0, nca1);
;       ev_compute(vA, ca0, ca1, ybuf + (size_t)tA * 1024 + 128 * cs, lane);
;       ev_load(vb8, na0, na1, cs, lane, vA);
.LBB0_567:
	s_waitcnt lgkmcnt(1)
	v_lshrrev_b32_e32 v2, s17, v1
	v_and_b32_e32 v2, 1, v2
	v_cmp_eq_u32_e32 vcc, 0, v2
	s_or_b64 s[0:1], s[14:15], vcc
	s_and_b64 vcc, exec, s[0:1]
	s_cbranch_vccnz .LBB0_566
	global_load_dword v2, v[134:135], off
	global_load_dword v3, v[136:137], off
	s_and_b64 vcc, exec, s[12:13]
	s_waitcnt vmcnt(1)
	ds_bpermute_b32 v58, v168, v2
	ds_bpermute_b32 v60, v168, v2 offset:32
	ds_bpermute_b32 v50, v168, v2 offset:64
	ds_bpermute_b32 v52, v168, v2 offset:96
	ds_bpermute_b32 v42, v168, v2 offset:128
	ds_bpermute_b32 v44, v168, v2 offset:160
	ds_bpermute_b32 v34, v168, v2 offset:192
	ds_bpermute_b32 v36, v168, v2 offset:224
	s_waitcnt vmcnt(0)
	ds_bpermute_b32 v26, v168, v3
	ds_bpermute_b32 v28, v168, v3 offset:32
	ds_bpermute_b32 v18, v168, v3 offset:64
	ds_bpermute_b32 v20, v168, v3 offset:96
	ds_bpermute_b32 v10, v168, v3 offset:128
	ds_bpermute_b32 v12, v168, v3 offset:160
	ds_bpermute_b32 v2, v168, v3 offset:192
	s_waitcnt lgkmcnt(14)
	ds_bpermute_b32 v4, v168, v3 offset:224
	s_cbranch_vccnz .LBB0_566
	s_lshl_b32 s24, s17, 7
	v_and_b32_e32 v204, 7, v0
	v_lshl_add_u32 v204, v204, 4, s24
	s_add_u32 s98, s72, 0x6c00000
	s_addc_u32 s99, s73, 0
	s_waitcnt lgkmcnt(0)
	v_lshl_add_u64 v[150:151], v[130:131], 0, s[24:25]
	v_lshl_add_u32 v14, v4, 10, v204
	v_lshl_add_u32 v16, v2, 10, v204
	v_lshl_add_u32 v22, v12, 10, v204
	v_lshl_add_u32 v24, v10, 10, v204
	v_lshl_add_u32 v30, v20, 10, v204
	v_lshl_add_u32 v32, v18, 10, v204
	v_lshl_add_u32 v38, v28, 10, v204
	v_lshl_add_u32 v40, v26, 10, v204
	v_lshl_add_u32 v46, v36, 10, v204
	v_lshl_add_u32 v48, v34, 10, v204
	v_lshl_add_u32 v54, v44, 10, v204
	v_lshl_add_u32 v56, v42, 10, v204
	v_lshl_add_u32 v62, v52, 10, v204
	v_lshl_add_u32 v64, v50, 10, v204
	v_lshl_add_u32 v66, v60, 10, v204
	global_load_dwordx4 v[2:5], v14, s[98:99]
	global_load_dwordx4 v[6:9], v16, s[98:99]
	global_load_dwordx4 v[10:13], v22, s[98:99]
	s_nop 0
	global_load_dwordx4 v[14:17], v24, s[98:99]
	global_load_dwordx4 v[18:21], v30, s[98:99]
	s_nop 0
	global_load_dwordx4 v[22:25], v32, s[98:99]
	global_load_dwordx4 v[26:29], v38, s[98:99]
	s_nop 0
	global_load_dwordx4 v[30:33], v40, s[98:99]
	global_load_dwordx4 v[34:37], v46, s[98:99]
	s_nop 0
	global_load_dwordx4 v[38:41], v48, s[98:99]
	global_load_dwordx4 v[42:45], v54, s[98:99]
	s_nop 0
	global_load_dwordx4 v[46:49], v56, s[98:99]
	global_load_dwordx4 v[50:53], v62, s[98:99]
	s_nop 0
	global_load_dwordx4 v[54:57], v64, s[98:99]
	v_lshl_add_u32 v68, v58, 10, v204
	global_load_dwordx4 v[58:61], v66, s[98:99]
	global_load_dwordx4 v[62:65], v68, s[98:99]
	global_load_dword v180, v[138:139], off
	global_load_dword v183, v[140:141], off
	global_load_dword v184, v[142:143], off
	global_load_dword v185, v[144:145], off
	global_load_dword v154, v[146:147], off
	global_load_dword v155, v[148:149], off
	v_and_b32_e32 v67, 64, v167
	v_xor_b32_e32 v66, 32, v167
	v_add_u32_e32 v67, 64, v67
	v_cmp_lt_i32_e32 vcc, v66, v67
	s_lshl_b32 s24, s17, 8
	v_or_b32_e32 v175, 0xc0, v168
	v_cndmask_b32_e32 v66, v167, v66, vcc
	v_lshlrev_b32_e32 v177, 2, v66
	v_xor_b32_e32 v66, 16, v167
	v_cmp_lt_i32_e32 vcc, v66, v67
	v_or_b32_e32 v176, 0xe0, v168
	v_lshl_add_u64 v[152:153], v[132:133], 0, s[24:25]
	v_cndmask_b32_e32 v66, v167, v66, vcc
	v_lshlrev_b32_e32 v178, 2, v66
	v_xor_b32_e32 v66, 8, v167
	v_cmp_lt_i32_e32 vcc, v66, v67
	s_mov_b32 s19, 3
	s_mov_b32 s36, s16
	v_cndmask_b32_e32 v66, v167, v66, vcc
	v_lshlrev_b32_e32 v179, 2, v66
	s_mov_b32 s30, s18
.LBB0_570:
	s_add_i32 s24, s19, -1
	s_min_i32 s0, s24, s41
	s_waitcnt vmcnt(2)
	ds_bpermute_b32 v66, v168, v185
	s_mul_i32 s0, s0, s39
	s_add_i32 s0, s0, s33
	s_lshl_b32 s0, s0, 3
	s_add_i32 s20, s0, s38
	s_ashr_i32 s21, s20, 31
	s_waitcnt lgkmcnt(0)
	s_lshl_b64 s[0:1], s[20:21], 9
	v_or_b32_e32 v158, s0, v174
	v_mov_b32_e32 v159, s1
	v_lshl_add_u32 v66, v66, 10, v204
	v_lshl_add_u64 v[156:157], s[26:27], 0, v[158:159]
	global_load_dwordx4 v[126:129], v66, s[98:99]
	v_or_b32_e32 v160, 0x100, v158
	global_load_dword v157, v[156:157], off
	ds_bpermute_b32 v66, v169, v185
	v_lshl_add_u64 v[158:159], s[28:29], 0, v[158:159]
	global_load_dword v181, v[158:159], off
	v_mov_b32_e32 v161, s1
	v_lshl_add_u64 v[158:159], s[28:29], 0, v[160:161]
	s_waitcnt lgkmcnt(0)
	v_lshl_add_u32 v66, v66, 10, v204
	global_load_dwordx4 v[122:125], v66, s[98:99]
	ds_bpermute_b32 v66, v170, v185
	global_load_dword v182, v[158:159], off
	v_lshl_add_u64 v[162:163], s[26:27], 0, v[160:161]
	s_waitcnt vmcnt(5)
	ds_bpermute_b32 v158, v168, v155
	v_cvt_pk_f32_fp8_e32 v[160:161], v62
	s_waitcnt lgkmcnt(1)
	v_lshl_add_u32 v66, v66, 10, v204
	global_load_dwordx4 v[118:121], v66, s[98:99]
	ds_bpermute_b32 v66, v171, v185
	global_load_dword v156, v[162:163], off
	v_cvt_pk_f32_fp8_sdwa v[162:163], v62 src0_sel:WORD_1
	v_cvt_pk_f32_fp8_e32 v[164:165], v63
	v_cvt_pk_f32_fp8_sdwa v[62:63], v63 src0_sel:WORD_1
	s_waitcnt lgkmcnt(0)
	v_lshl_add_u32 v66, v66, 10, v204
	global_load_dwordx4 v[114:117], v66, s[98:99]
	ds_bpermute_b32 v66, v172, v185
	v_cvt_pk_f32_fp8_sdwa v[186:187], v64 src0_sel:WORD_1
	v_cvt_pk_f32_fp8_e32 v[188:189], v65
	v_pk_fma_f32 v[160:161], v[160:161], v[158:159], 0 op_sel_hi:[1,0,0]
	v_pk_fma_f32 v[162:163], v[162:163], v[158:159], 0 op_sel_hi:[1,0,0]
	s_waitcnt lgkmcnt(0)
	v_lshl_add_u32 v66, v66, 10, v204
	global_load_dwordx4 v[110:113], v66, s[98:99]
	ds_bpermute_b32 v66, v173, v185
	v_pk_fma_f32 v[164:165], v[164:165], v[158:159], 0 op_sel_hi:[1,0,0]
	v_pk_fma_f32 v[62:63], v[62:63], v[158:159], 0 op_sel_hi:[1,0,0]
	v_pk_fma_f32 v[186:187], v[186:187], v[158:159], 0 op_sel_hi:[1,0,0]
	v_pk_fma_f32 v[188:189], v[188:189], v[158:159], 0 op_sel_hi:[1,0,0]
	s_waitcnt lgkmcnt(0)
; DI void ev_load(const unsigned char* __restrict__ vb8, const int id0, const int id1, const int cs, const int lane, uint4 (&v)[16]) {
; #pragma unroll
;   for (int i = 0; i < 16; ++i) {
;     const int id = __shfl(i < 8 ? id0 : id1, (8 * i + (lane >> 3)) & 63, 64);
;     v[i] = *(const uint4*)(vb8 + (size_t)id * 1024 + 128 * cs + 16 * (lane & 7));
;   }
; }
; DI void ev_compute(const uint4 (&v)[16], const float c0, const float c1, u16* __restrict__ yrow, const int lane) {
;   f32x2 acc[8];
; #pragma unroll
;   for (int k = 0; k < 8; ++k) acc[k] = f32x2{0.f, 0.f};
; #pragma unroll
;   for (int i = 0; i < 16; ++i) {
;     const float c = __shfl(i < 8 ? c0 : c1, (8 * i + (lane >> 3)) & 63, 64);
;     const f32x2 cc = f32x2{c, c};
;     f32x2 vf[8];
;     fp8x16_to_f32(v[i], vf);
; #pragma unroll
;     for (int k = 0; k < 8; ++k) acc[k] = __builtin_elementwise_fma(vf[k], cc, acc[k]);
;   }
	v_lshl_add_u32 v66, v66, 10, v204
	global_load_dwordx4 v[106:109], v66, s[98:99]
	ds_bpermute_b32 v66, v175, v185
	v_cvt_pk_f32_fp8_e32 v[196:197], v60
	v_cvt_pk_f32_fp8_sdwa v[198:199], v60 src0_sel:WORD_1
	v_cvt_pk_f32_fp8_e32 v[202:203], v61
	v_cvt_pk_f32_fp8_sdwa v[60:61], v61 src0_sel:WORD_1
	s_waitcnt lgkmcnt(0)
	v_lshl_add_u32 v66, v66, 10, v204
	global_load_dwordx4 v[102:105], v66, s[98:99]
	ds_bpermute_b32 v66, v176, v185
	v_cvt_pk_f32_fp8_e32 v[190:191], v58
	v_cvt_pk_f32_fp8_sdwa v[192:193], v58 src0_sel:WORD_1
	v_cvt_pk_f32_fp8_e32 v[194:195], v59
	v_cvt_pk_f32_fp8_sdwa v[58:59], v59 src0_sel:WORD_1
	s_waitcnt lgkmcnt(0)
	v_lshl_add_u32 v66, v66, 10, v204
	global_load_dwordx4 v[98:101], v66, s[98:99]
	ds_bpermute_b32 v66, v168, v184
	s_ashr_i32 s37, s36, 31
	s_lshl_b64 s[34:35], s[36:37], 11
	s_min_i32 s0, s19, s41
	s_mul_i32 s0, s0, s39
	s_waitcnt lgkmcnt(0)
	v_lshl_add_u32 v66, v66, 10, v204
	global_load_dwordx4 v[94:97], v66, s[98:99]
	ds_bpermute_b32 v66, v169, v184
	s_add_i32 s0, s0, s33
	s_lshl_b32 s0, s0, 3
	ds_bpermute_b32 v166, v169, v183
	s_ashr_i32 s31, s30, 31
	s_waitcnt lgkmcnt(1)
	v_lshl_add_u32 v66, v66, 10, v204
	global_load_dwordx4 v[90:93], v66, s[98:99]
	ds_bpermute_b32 v66, v170, v184
	s_lshl_b64 s[30:31], s[30:31], 11
	s_add_i32 s19, s19, 2
	s_mov_b32 s36, s20
	s_waitcnt lgkmcnt(0)
	v_lshl_add_u32 v66, v66, 10, v204
	global_load_dwordx4 v[86:89], v66, s[98:99]
	ds_bpermute_b32 v66, v171, v184
	s_waitcnt lgkmcnt(0)
	v_lshl_add_u32 v66, v66, 10, v204
	global_load_dwordx4 v[82:85], v66, s[98:99]
	ds_bpermute_b32 v66, v172, v184
	s_waitcnt lgkmcnt(0)
	v_lshl_add_u32 v66, v66, 10, v204
	global_load_dwordx4 v[78:81], v66, s[98:99]
	ds_bpermute_b32 v66, v173, v184
	s_waitcnt lgkmcnt(0)
	v_lshl_add_u32 v66, v66, 10, v204
	global_load_dwordx4 v[74:77], v66, s[98:99]
	ds_bpermute_b32 v66, v175, v184
	s_waitcnt lgkmcnt(0)
	v_lshl_add_u32 v66, v66, 10, v204
	global_load_dwordx4 v[70:73], v66, s[98:99]
	ds_bpermute_b32 v66, v176, v184
	v_cvt_pk_f32_fp8_e32 v[184:185], v64
	v_cvt_pk_f32_fp8_sdwa v[64:65], v65 src0_sel:WORD_1
	v_pk_fma_f32 v[184:185], v[184:185], v[158:159], 0 op_sel_hi:[1,0,0]
	v_pk_fma_f32 v[64:65], v[64:65], v[158:159], 0 op_sel_hi:[1,0,0]
	ds_bpermute_b32 v158, v169, v155
	s_waitcnt lgkmcnt(1)
	v_lshl_add_u32 v66, v66, 10, v204
	global_load_dwordx4 v[66:69], v66, s[98:99]
	s_waitcnt lgkmcnt(0)
	v_pk_fma_f32 v[60:61], v[60:61], v[158:159], v[64:65] op_sel_hi:[1,0,1]
	ds_bpermute_b32 v64, v170, v155
	v_pk_fma_f32 v[162:163], v[192:193], v[158:159], v[162:163] op_sel_hi:[1,0,1]
	v_pk_fma_f32 v[164:165], v[194:195], v[158:159], v[164:165] op_sel_hi:[1,0,1]
	v_pk_fma_f32 v[58:59], v[58:59], v[158:159], v[62:63] op_sel_hi:[1,0,1]
	v_pk_fma_f32 v[62:63], v[196:197], v[158:159], v[184:185] op_sel_hi:[1,0,1]
	v_cvt_pk_f32_fp8_e32 v[192:193], v56
	v_cvt_pk_f32_fp8_sdwa v[194:195], v56 src0_sel:WORD_1
	v_cvt_pk_f32_fp8_e32 v[196:197], v57
	v_cvt_pk_f32_fp8_sdwa v[56:57], v57 src0_sel:WORD_1
	v_pk_fma_f32 v[160:161], v[190:191], v[158:159], v[160:161] op_sel_hi:[1,0,1]
	v_pk_fma_f32 v[184:185], v[198:199], v[158:159], v[186:187] op_sel_hi:[1,0,1]
	v_pk_fma_f32 v[186:187], v[202:203], v[158:159], v[188:189] op_sel_hi:[1,0,1]
	v_cvt_pk_f32_fp8_e32 v[158:159], v54
	v_cvt_pk_f32_fp8_sdwa v[188:189], v54 src0_sel:WORD_1
	v_cvt_pk_f32_fp8_e32 v[190:191], v55
	v_cvt_pk_f32_fp8_sdwa v[54:55], v55 src0_sel:WORD_1
	s_waitcnt lgkmcnt(0)
	v_pk_fma_f32 v[56:57], v[56:57], v[64:65], v[60:61] op_sel_hi:[1,0,1]
	ds_bpermute_b32 v60, v171, v155
	v_pk_fma_f32 v[158:159], v[158:159], v[64:65], v[160:161] op_sel_hi:[1,0,1]
	v_pk_fma_f32 v[160:161], v[188:189], v[64:65], v[162:163] op_sel_hi:[1,0,1]
	v_pk_fma_f32 v[162:163], v[190:191], v[64:65], v[164:165] op_sel_hi:[1,0,1]
	v_pk_fma_f32 v[54:55], v[54:55], v[64:65], v[58:59] op_sel_hi:[1,0,1]
	v_pk_fma_f32 v[58:59], v[192:193], v[64:65], v[62:63] op_sel_hi:[1,0,1]
	v_cvt_pk_f32_fp8_e32 v[188:189], v52
	v_cvt_pk_f32_fp8_sdwa v[190:191], v52 src0_sel:WORD_1
	v_cvt_pk_f32_fp8_e32 v[192:193], v53
	v_cvt_pk_f32_fp8_sdwa v[52:53], v53 src0_sel:WORD_1
	v_pk_fma_f32 v[62:63], v[194:195], v[64:65], v[184:185] op_sel_hi:[1,0,1]
	v_pk_fma_f32 v[164:165], v[196:197], v[64:65], v[186:187] op_sel_hi:[1,0,1]
	v_cvt_pk_f32_fp8_e32 v[64:65], v50
	v_cvt_pk_f32_fp8_sdwa v[184:185], v50 src0_sel:WORD_1
	v_cvt_pk_f32_fp8_e32 v[186:187], v51
	v_cvt_pk_f32_fp8_sdwa v[50:51], v51 src0_sel:WORD_1
	s_waitcnt lgkmcnt(0)
	v_pk_fma_f32 v[52:53], v[52:53], v[60:61], v[56:57] op_sel_hi:[1,0,1]
	ds_bpermute_b32 v56, v172, v155
	v_pk_fma_f32 v[64:65], v[64:65], v[60:61], v[158:159] op_sel_hi:[1,0,1]
	v_pk_fma_f32 v[158:159], v[184:185], v[60:61], v[160:161] op_sel_hi:[1,0,1]
	v_pk_fma_f32 v[160:161], v[186:187], v[60:61], v[162:163] op_sel_hi:[1,0,1]
	v_pk_fma_f32 v[50:51], v[50:51], v[60:61], v[54:55] op_sel_hi:[1,0,1]
	v_pk_fma_f32 v[54:55], v[188:189], v[60:61], v[58:59] op_sel_hi:[1,0,1]
	v_cvt_pk_f32_fp8_e32 v[184:185], v48
	v_cvt_pk_f32_fp8_sdwa v[186:187], v48 src0_sel:WORD_1
	v_cvt_pk_f32_fp8_e32 v[188:189], v49
	v_cvt_pk_f32_fp8_sdwa v[48:49], v49 src0_sel:WORD_1
	v_pk_fma_f32 v[58:59], v[190:191], v[60:61], v[62:63] op_sel_hi:[1,0,1]
	v_pk_fma_f32 v[62:63], v[192:193], v[60:61], v[164:165] op_sel_hi:[1,0,1]
	v_cvt_pk_f32_fp8_e32 v[60:61], v46
	v_cvt_pk_f32_fp8_sdwa v[162:163], v46 src0_sel:WORD_1
	v_cvt_pk_f32_fp8_e32 v[164:165], v47
	v_cvt_pk_f32_fp8_sdwa v[46:47], v47 src0_sel:WORD_1
	s_waitcnt lgkmcnt(0)
; DI void ev_compute(const uint4 (&v)[16], const float c0, const float c1, u16* __restrict__ yrow, const int lane) {
;   f32x2 acc[8];
; #pragma unroll
;   for (int k = 0; k < 8; ++k) acc[k] = f32x2{0.f, 0.f};
; #pragma unroll
;   for (int i = 0; i < 16; ++i) {
;     const float c = __shfl(i < 8 ? c0 : c1, (8 * i + (lane >> 3)) & 63, 64);
;     const f32x2 cc = f32x2{c, c};
;     f32x2 vf[8];
;     fp8x16_to_f32(v[i], vf);
; #pragma unroll
;     for (int k = 0; k < 8; ++k) acc[k] = __builtin_elementwise_fma(vf[k], cc, acc[k]);
;   }
	v_pk_fma_f32 v[48:49], v[48:49], v[56:57], v[52:53] op_sel_hi:[1,0,1]
	ds_bpermute_b32 v52, v173, v155
	v_pk_fma_f32 v[60:61], v[60:61], v[56:57], v[64:65] op_sel_hi:[1,0,1]
	v_pk_fma_f32 v[64:65], v[162:163], v[56:57], v[158:159] op_sel_hi:[1,0,1]
	v_pk_fma_f32 v[158:159], v[164:165], v[56:57], v[160:161] op_sel_hi:[1,0,1]
	v_pk_fma_f32 v[46:47], v[46:47], v[56:57], v[50:51] op_sel_hi:[1,0,1]
	v_pk_fma_f32 v[50:51], v[184:185], v[56:57], v[54:55] op_sel_hi:[1,0,1]
	v_cvt_pk_f32_fp8_e32 v[162:163], v44
	v_cvt_pk_f32_fp8_sdwa v[164:165], v44 src0_sel:WORD_1
	v_cvt_pk_f32_fp8_e32 v[184:185], v45
	v_cvt_pk_f32_fp8_sdwa v[44:45], v45 src0_sel:WORD_1
	v_pk_fma_f32 v[54:55], v[186:187], v[56:57], v[58:59] op_sel_hi:[1,0,1]
	v_pk_fma_f32 v[58:59], v[188:189], v[56:57], v[62:63] op_sel_hi:[1,0,1]
	v_cvt_pk_f32_fp8_e32 v[56:57], v42
	v_cvt_pk_f32_fp8_sdwa v[62:63], v42 src0_sel:WORD_1
	v_cvt_pk_f32_fp8_e32 v[160:161], v43
	v_cvt_pk_f32_fp8_sdwa v[42:43], v43 src0_sel:WORD_1
	s_waitcnt lgkmcnt(0)
	v_pk_fma_f32 v[44:45], v[44:45], v[52:53], v[48:49] op_sel_hi:[1,0,1]
	ds_bpermute_b32 v48, v175, v155
	v_pk_fma_f32 v[56:57], v[56:57], v[52:53], v[60:61] op_sel_hi:[1,0,1]
	v_pk_fma_f32 v[60:61], v[62:63], v[52:53], v[64:65] op_sel_hi:[1,0,1]
	v_pk_fma_f32 v[62:63], v[160:161], v[52:53], v[158:159] op_sel_hi:[1,0,1]
	v_pk_fma_f32 v[42:43], v[42:43], v[52:53], v[46:47] op_sel_hi:[1,0,1]
	v_pk_fma_f32 v[46:47], v[162:163], v[52:53], v[50:51] op_sel_hi:[1,0,1]
	v_cvt_pk_f32_fp8_e32 v[158:159], v40
	v_cvt_pk_f32_fp8_sdwa v[160:161], v40 src0_sel:WORD_1
	v_cvt_pk_f32_fp8_e32 v[162:163], v41
	v_cvt_pk_f32_fp8_sdwa v[40:41], v41 src0_sel:WORD_1
	v_pk_fma_f32 v[50:51], v[164:165], v[52:53], v[54:55] op_sel_hi:[1,0,1]
	v_pk_fma_f32 v[54:55], v[184:185], v[52:53], v[58:59] op_sel_hi:[1,0,1]
	v_cvt_pk_f32_fp8_e32 v[52:53], v38
	v_cvt_pk_f32_fp8_sdwa v[58:59], v38 src0_sel:WORD_1
	v_cvt_pk_f32_fp8_e32 v[64:65], v39
	v_cvt_pk_f32_fp8_sdwa v[38:39], v39 src0_sel:WORD_1
	s_waitcnt lgkmcnt(0)
	v_pk_fma_f32 v[40:41], v[40:41], v[48:49], v[44:45] op_sel_hi:[1,0,1]
	ds_bpermute_b32 v44, v176, v155
	v_pk_fma_f32 v[52:53], v[52:53], v[48:49], v[56:57] op_sel_hi:[1,0,1]
	v_pk_fma_f32 v[56:57], v[58:59], v[48:49], v[60:61] op_sel_hi:[1,0,1]
	v_pk_fma_f32 v[58:59], v[64:65], v[48:49], v[62:63] op_sel_hi:[1,0,1]
	v_pk_fma_f32 v[38:39], v[38:39], v[48:49], v[42:43] op_sel_hi:[1,0,1]
	v_pk_fma_f32 v[42:43], v[158:159], v[48:49], v[46:47] op_sel_hi:[1,0,1]
	v_cvt_pk_f32_fp8_e32 v[62:63], v36
	v_cvt_pk_f32_fp8_sdwa v[64:65], v36 src0_sel:WORD_1
	v_cvt_pk_f32_fp8_e32 v[158:159], v37
	v_cvt_pk_f32_fp8_sdwa v[36:37], v37 src0_sel:WORD_1
	v_pk_fma_f32 v[46:47], v[160:161], v[48:49], v[50:51] op_sel_hi:[1,0,1]
	v_pk_fma_f32 v[50:51], v[162:163], v[48:49], v[54:55] op_sel_hi:[1,0,1]
	v_cvt_pk_f32_fp8_e32 v[48:49], v34
	v_cvt_pk_f32_fp8_sdwa v[54:55], v34 src0_sel:WORD_1
	v_cvt_pk_f32_fp8_e32 v[60:61], v35
	v_cvt_pk_f32_fp8_sdwa v[34:35], v35 src0_sel:WORD_1
	s_waitcnt lgkmcnt(0)
	v_pk_fma_f32 v[36:37], v[36:37], v[44:45], v[40:41] op_sel_hi:[1,0,1]
	ds_bpermute_b32 v40, v168, v154
	v_pk_fma_f32 v[48:49], v[48:49], v[44:45], v[52:53] op_sel_hi:[1,0,1]
	v_pk_fma_f32 v[52:53], v[54:55], v[44:45], v[56:57] op_sel_hi:[1,0,1]
	v_pk_fma_f32 v[54:55], v[60:61], v[44:45], v[58:59] op_sel_hi:[1,0,1]
	v_pk_fma_f32 v[34:35], v[34:35], v[44:45], v[38:39] op_sel_hi:[1,0,1]
	v_pk_fma_f32 v[38:39], v[62:63], v[44:45], v[42:43] op_sel_hi:[1,0,1]
	v_cvt_pk_f32_fp8_e32 v[58:59], v32
	v_cvt_pk_f32_fp8_sdwa v[60:61], v32 src0_sel:WORD_1
	v_cvt_pk_f32_fp8_e32 v[62:63], v33
	v_cvt_pk_f32_fp8_sdwa v[32:33], v33 src0_sel:WORD_1
	v_pk_fma_f32 v[42:43], v[64:65], v[44:45], v[46:47] op_sel_hi:[1,0,1]
	v_pk_fma_f32 v[46:47], v[158:159], v[44:45], v[50:51] op_sel_hi:[1,0,1]
	v_cvt_pk_f32_fp8_e32 v[44:45], v30
	v_cvt_pk_f32_fp8_sdwa v[50:51], v30 src0_sel:WORD_1
	v_cvt_pk_f32_fp8_e32 v[56:57], v31
	v_cvt_pk_f32_fp8_sdwa v[30:31], v31 src0_sel:WORD_1
	s_waitcnt lgkmcnt(0)
	v_pk_fma_f32 v[32:33], v[32:33], v[40:41], v[36:37] op_sel_hi:[1,0,1]
	ds_bpermute_b32 v36, v169, v154
	v_pk_fma_f32 v[44:45], v[44:45], v[40:41], v[48:49] op_sel_hi:[1,0,1]
	v_pk_fma_f32 v[48:49], v[50:51], v[40:41], v[52:53] op_sel_hi:[1,0,1]
	v_pk_fma_f32 v[50:51], v[56:57], v[40:41], v[54:55] op_sel_hi:[1,0,1]
	v_pk_fma_f32 v[30:31], v[30:31], v[40:41], v[34:35] op_sel_hi:[1,0,1]
	v_pk_fma_f32 v[34:35], v[58:59], v[40:41], v[38:39] op_sel_hi:[1,0,1]
	v_cvt_pk_f32_fp8_e32 v[54:55], v28
	v_cvt_pk_f32_fp8_sdwa v[56:57], v28 src0_sel:WORD_1
	v_cvt_pk_f32_fp8_e32 v[58:59], v29
	v_cvt_pk_f32_fp8_sdwa v[28:29], v29 src0_sel:WORD_1
	v_pk_fma_f32 v[38:39], v[60:61], v[40:41], v[42:43] op_sel_hi:[1,0,1]
	v_pk_fma_f32 v[42:43], v[62:63], v[40:41], v[46:47] op_sel_hi:[1,0,1]
	v_cvt_pk_f32_fp8_e32 v[40:41], v26
	v_cvt_pk_f32_fp8_sdwa v[46:47], v26 src0_sel:WORD_1
	v_cvt_pk_f32_fp8_e32 v[52:53], v27
	v_cvt_pk_f32_fp8_sdwa v[26:27], v27 src0_sel:WORD_1
	s_waitcnt lgkmcnt(0)
	v_pk_fma_f32 v[28:29], v[28:29], v[36:37], v[32:33] op_sel_hi:[1,0,1]
	ds_bpermute_b32 v32, v170, v154
	v_pk_fma_f32 v[40:41], v[40:41], v[36:37], v[44:45] op_sel_hi:[1,0,1]
	v_pk_fma_f32 v[44:45], v[46:47], v[36:37], v[48:49] op_sel_hi:[1,0,1]
	v_pk_fma_f32 v[46:47], v[52:53], v[36:37], v[50:51] op_sel_hi:[1,0,1]
	v_pk_fma_f32 v[26:27], v[26:27], v[36:37], v[30:31] op_sel_hi:[1,0,1]
	v_pk_fma_f32 v[30:31], v[54:55], v[36:37], v[34:35] op_sel_hi:[1,0,1]
	v_cvt_pk_f32_fp8_e32 v[50:51], v24
	v_cvt_pk_f32_fp8_sdwa v[52:53], v24 src0_sel:WORD_1
	v_cvt_pk_f32_fp8_e32 v[54:55], v25
	v_cvt_pk_f32_fp8_sdwa v[24:25], v25 src0_sel:WORD_1
	v_pk_fma_f32 v[34:35], v[56:57], v[36:37], v[38:39] op_sel_hi:[1,0,1]
	v_pk_fma_f32 v[38:39], v[58:59], v[36:37], v[42:43] op_sel_hi:[1,0,1]
	v_cvt_pk_f32_fp8_e32 v[36:37], v22
	v_cvt_pk_f32_fp8_sdwa v[42:43], v22 src0_sel:WORD_1
	v_cvt_pk_f32_fp8_e32 v[48:49], v23
	v_cvt_pk_f32_fp8_sdwa v[22:23], v23 src0_sel:WORD_1
	s_waitcnt lgkmcnt(0)
; DI void ev_compute(const uint4 (&v)[16], const float c0, const float c1, u16* __restrict__ yrow, const int lane) {
;     ...
;   for (int i = 0; i < 16; ++i) {
;     const float c = __shfl(i < 8 ? c0 : c1, (8 * i + (lane >> 3)) & 63, 64);
;     const f32x2 cc = f32x2{c, c};
;     f32x2 vf[8];
;     fp8x16_to_f32(v[i], vf);
; #pragma unroll
;     for (int k = 0; k < 8; ++k) acc[k] = __builtin_elementwise_fma(vf[k], cc, acc[k]);
;   }
;   float a[16];
; #pragma unroll
;   for (int k = 0; k < 8; ++k) { a[2 * k] = acc[k][0]; a[2 * k + 1] = acc[k][1]; }
;   float q8[8], q4[4], q2[2];
;   const bool b5 = lane & 32, b4 = lane & 16, b3 = lane & 8;
; #pragma unroll
;   for (int j = 0; j < 8; ++j) { const float keep = b5 ? a[8 + j] : a[j], send = b5 ? a[j] : a[8 + j]; q8[j] = keep + __shfl_xor(send, 32, 64); }
; #pragma unroll
;   for (int j = 0; j < 4; ++j) { const float keep = b4 ? q8[4 + j] : q8[j], send = b4 ? q8[j] : q8[4 + j]; q4[j] = keep + __shfl_xor(send, 16, 64); }
; #pragma unroll
;   for (int j = 0; j < 2; ++j) { const float keep = b3 ? q4[2 + j] : q4[j], send = b3 ? q4[j] : q4[2 + j]; q2[j] = keep + __shfl_xor(send, 8, 64); }
	v_pk_fma_f32 v[24:25], v[24:25], v[32:33], v[28:29] op_sel_hi:[1,0,1]
	ds_bpermute_b32 v28, v171, v154
	v_pk_fma_f32 v[36:37], v[36:37], v[32:33], v[40:41] op_sel_hi:[1,0,1]
	v_pk_fma_f32 v[40:41], v[42:43], v[32:33], v[44:45] op_sel_hi:[1,0,1]
	v_pk_fma_f32 v[42:43], v[48:49], v[32:33], v[46:47] op_sel_hi:[1,0,1]
	v_pk_fma_f32 v[22:23], v[22:23], v[32:33], v[26:27] op_sel_hi:[1,0,1]
	v_pk_fma_f32 v[26:27], v[50:51], v[32:33], v[30:31] op_sel_hi:[1,0,1]
	v_cvt_pk_f32_fp8_e32 v[46:47], v20
	v_cvt_pk_f32_fp8_sdwa v[48:49], v20 src0_sel:WORD_1
	v_cvt_pk_f32_fp8_e32 v[50:51], v21
	v_cvt_pk_f32_fp8_sdwa v[20:21], v21 src0_sel:WORD_1
	v_pk_fma_f32 v[30:31], v[52:53], v[32:33], v[34:35] op_sel_hi:[1,0,1]
	v_pk_fma_f32 v[34:35], v[54:55], v[32:33], v[38:39] op_sel_hi:[1,0,1]
	v_cvt_pk_f32_fp8_e32 v[32:33], v18
	v_cvt_pk_f32_fp8_sdwa v[38:39], v18 src0_sel:WORD_1
	v_cvt_pk_f32_fp8_e32 v[44:45], v19
	v_cvt_pk_f32_fp8_sdwa v[18:19], v19 src0_sel:WORD_1
	s_waitcnt lgkmcnt(0)
	v_pk_fma_f32 v[20:21], v[20:21], v[28:29], v[24:25] op_sel_hi:[1,0,1]
	ds_bpermute_b32 v24, v172, v154
	v_pk_fma_f32 v[32:33], v[32:33], v[28:29], v[36:37] op_sel_hi:[1,0,1]
	v_pk_fma_f32 v[36:37], v[38:39], v[28:29], v[40:41] op_sel_hi:[1,0,1]
	v_pk_fma_f32 v[38:39], v[44:45], v[28:29], v[42:43] op_sel_hi:[1,0,1]
	v_pk_fma_f32 v[18:19], v[18:19], v[28:29], v[22:23] op_sel_hi:[1,0,1]
	v_pk_fma_f32 v[22:23], v[46:47], v[28:29], v[26:27] op_sel_hi:[1,0,1]
	v_cvt_pk_f32_fp8_e32 v[42:43], v16
	v_cvt_pk_f32_fp8_sdwa v[44:45], v16 src0_sel:WORD_1
	v_cvt_pk_f32_fp8_e32 v[46:47], v17
	v_cvt_pk_f32_fp8_sdwa v[16:17], v17 src0_sel:WORD_1
	v_pk_fma_f32 v[26:27], v[48:49], v[28:29], v[30:31] op_sel_hi:[1,0,1]
	v_pk_fma_f32 v[30:31], v[50:51], v[28:29], v[34:35] op_sel_hi:[1,0,1]
	v_cvt_pk_f32_fp8_e32 v[28:29], v14
	v_cvt_pk_f32_fp8_sdwa v[34:35], v14 src0_sel:WORD_1
	v_cvt_pk_f32_fp8_e32 v[40:41], v15
	v_cvt_pk_f32_fp8_sdwa v[14:15], v15 src0_sel:WORD_1
	s_waitcnt lgkmcnt(0)
	v_pk_fma_f32 v[16:17], v[16:17], v[24:25], v[20:21] op_sel_hi:[1,0,1]
	ds_bpermute_b32 v20, v173, v154
	v_pk_fma_f32 v[28:29], v[28:29], v[24:25], v[32:33] op_sel_hi:[1,0,1]
	v_pk_fma_f32 v[32:33], v[34:35], v[24:25], v[36:37] op_sel_hi:[1,0,1]
	v_pk_fma_f32 v[34:35], v[40:41], v[24:25], v[38:39] op_sel_hi:[1,0,1]
	v_pk_fma_f32 v[14:15], v[14:15], v[24:25], v[18:19] op_sel_hi:[1,0,1]
	v_pk_fma_f32 v[18:19], v[42:43], v[24:25], v[22:23] op_sel_hi:[1,0,1]
	v_cvt_pk_f32_fp8_e32 v[38:39], v12
	v_cvt_pk_f32_fp8_sdwa v[40:41], v12 src0_sel:WORD_1
	v_cvt_pk_f32_fp8_e32 v[42:43], v13
	v_cvt_pk_f32_fp8_sdwa v[12:13], v13 src0_sel:WORD_1
	v_pk_fma_f32 v[22:23], v[44:45], v[24:25], v[26:27] op_sel_hi:[1,0,1]
	v_pk_fma_f32 v[26:27], v[46:47], v[24:25], v[30:31] op_sel_hi:[1,0,1]
	v_cvt_pk_f32_fp8_e32 v[24:25], v10
	v_cvt_pk_f32_fp8_sdwa v[30:31], v10 src0_sel:WORD_1
	v_cvt_pk_f32_fp8_e32 v[36:37], v11
	v_cvt_pk_f32_fp8_sdwa v[10:11], v11 src0_sel:WORD_1
	s_waitcnt lgkmcnt(0)
	v_pk_fma_f32 v[12:13], v[12:13], v[20:21], v[16:17] op_sel_hi:[1,0,1]
	ds_bpermute_b32 v16, v175, v154
	v_pk_fma_f32 v[24:25], v[24:25], v[20:21], v[28:29] op_sel_hi:[1,0,1]
	v_pk_fma_f32 v[28:29], v[30:31], v[20:21], v[32:33] op_sel_hi:[1,0,1]
	v_pk_fma_f32 v[30:31], v[36:37], v[20:21], v[34:35] op_sel_hi:[1,0,1]
	v_pk_fma_f32 v[10:11], v[10:11], v[20:21], v[14:15] op_sel_hi:[1,0,1]
	v_pk_fma_f32 v[14:15], v[38:39], v[20:21], v[18:19] op_sel_hi:[1,0,1]
	v_cvt_pk_f32_fp8_e32 v[34:35], v8
	v_cvt_pk_f32_fp8_sdwa v[36:37], v8 src0_sel:WORD_1
	v_cvt_pk_f32_fp8_e32 v[38:39], v9
	v_cvt_pk_f32_fp8_sdwa v[8:9], v9 src0_sel:WORD_1
	v_pk_fma_f32 v[18:19], v[40:41], v[20:21], v[22:23] op_sel_hi:[1,0,1]
	v_pk_fma_f32 v[22:23], v[42:43], v[20:21], v[26:27] op_sel_hi:[1,0,1]
	v_cvt_pk_f32_fp8_e32 v[20:21], v6
	v_cvt_pk_f32_fp8_sdwa v[26:27], v6 src0_sel:WORD_1
	v_cvt_pk_f32_fp8_e32 v[32:33], v7
	v_cvt_pk_f32_fp8_sdwa v[6:7], v7 src0_sel:WORD_1
	s_waitcnt lgkmcnt(0)
	v_pk_fma_f32 v[8:9], v[8:9], v[16:17], v[12:13] op_sel_hi:[1,0,1]
	ds_bpermute_b32 v12, v176, v154
	v_pk_fma_f32 v[20:21], v[20:21], v[16:17], v[24:25] op_sel_hi:[1,0,1]
	v_pk_fma_f32 v[24:25], v[26:27], v[16:17], v[28:29] op_sel_hi:[1,0,1]
	v_pk_fma_f32 v[26:27], v[32:33], v[16:17], v[30:31] op_sel_hi:[1,0,1]
	v_pk_fma_f32 v[6:7], v[6:7], v[16:17], v[10:11] op_sel_hi:[1,0,1]
	v_pk_fma_f32 v[10:11], v[34:35], v[16:17], v[14:15] op_sel_hi:[1,0,1]
	v_pk_fma_f32 v[14:15], v[36:37], v[16:17], v[18:19] op_sel_hi:[1,0,1]
	v_pk_fma_f32 v[18:19], v[38:39], v[16:17], v[22:23] op_sel_hi:[1,0,1]
	v_cvt_pk_f32_fp8_e32 v[16:17], v2
	v_cvt_pk_f32_fp8_sdwa v[22:23], v2 src0_sel:WORD_1
	v_cvt_pk_f32_fp8_e32 v[28:29], v3
	v_cvt_pk_f32_fp8_sdwa v[2:3], v3 src0_sel:WORD_1
	v_cvt_pk_f32_fp8_e32 v[30:31], v4
	v_cvt_pk_f32_fp8_sdwa v[32:33], v4 src0_sel:WORD_1
	v_cvt_pk_f32_fp8_e32 v[34:35], v5
	v_cvt_pk_f32_fp8_sdwa v[4:5], v5 src0_sel:WORD_1
	s_waitcnt lgkmcnt(0)
	v_pk_fma_f32 v[16:17], v[16:17], v[12:13], v[20:21] op_sel_hi:[1,0,1]
	v_pk_fma_f32 v[2:3], v[2:3], v[12:13], v[6:7] op_sel_hi:[1,0,1]
	v_pk_fma_f32 v[6:7], v[30:31], v[12:13], v[10:11] op_sel_hi:[1,0,1]
	v_pk_fma_f32 v[20:21], v[22:23], v[12:13], v[24:25] op_sel_hi:[1,0,1]
	v_pk_fma_f32 v[22:23], v[28:29], v[12:13], v[26:27] op_sel_hi:[1,0,1]
	v_pk_fma_f32 v[10:11], v[32:33], v[12:13], v[14:15] op_sel_hi:[1,0,1]
	v_pk_fma_f32 v[14:15], v[34:35], v[12:13], v[18:19] op_sel_hi:[1,0,1]
	v_pk_fma_f32 v[4:5], v[4:5], v[12:13], v[8:9] op_sel_hi:[1,0,1]
	v_cndmask_b32_e64 v8, v16, v6, s[6:7]
	v_cndmask_b32_e64 v9, v17, v7, s[6:7]
	ds_bpermute_b32 v8, v177, v8
	ds_bpermute_b32 v9, v177, v9
	v_cndmask_b32_e64 v12, v20, v10, s[6:7]
	v_cndmask_b32_e64 v13, v21, v11, s[6:7]
	v_cndmask_b32_e64 v18, v22, v14, s[6:7]
	v_cndmask_b32_e64 v19, v23, v15, s[6:7]
	v_cndmask_b32_e64 v24, v2, v4, s[6:7]
	v_cndmask_b32_e64 v25, v3, v5, s[6:7]
	ds_bpermute_b32 v12, v177, v12
	ds_bpermute_b32 v13, v177, v13
	ds_bpermute_b32 v18, v177, v18
	ds_bpermute_b32 v19, v177, v19
	ds_bpermute_b32 v24, v177, v24
	ds_bpermute_b32 v25, v177, v25
	v_cndmask_b32_e64 v7, v7, v17, s[6:7]
	v_cndmask_b32_e64 v6, v6, v16, s[6:7]
	s_waitcnt lgkmcnt(6)
; DI unsigned pack2(float a, float b) { const f32x2 v = {a, b}; const bf16x2_t r = __builtin_convertvector(v, bf16x2_t); return __builtin_bit_cast(unsigned, r); }
; #define EV_IDS(t, i0, i1, c0, c1) do { i0 = sel_i[(size_t)(t) * 128 + lane]; i1 = sel_i[(size_t)(t) * 128 + 64 + lane]; \
;                                        c0 = cbuf[(size_t)(t) * 128 + lane]; c1 = cbuf[(size_t)(t) * 128 + 64 + lane]; } while (0)
; DI void ev_compute(const uint4 (&v)[16], const float c0, const float c1, u16* __restrict__ yrow, const int lane) {
;     ...
;   float a[16];
; #pragma unroll
;   for (int k = 0; k < 8; ++k) { a[2 * k] = acc[k][0]; a[2 * k + 1] = acc[k][1]; }
;   float q8[8], q4[4], q2[2];
;   const bool b5 = lane & 32, b4 = lane & 16, b3 = lane & 8;
; #pragma unroll
;   for (int j = 0; j < 8; ++j) { const float keep = b5 ? a[8 + j] : a[j], send = b5 ? a[j] : a[8 + j]; q8[j] = keep + __shfl_xor(send, 32, 64); }
; #pragma unroll
;   for (int j = 0; j < 4; ++j) { const float keep = b4 ? q8[4 + j] : q8[j], send = b4 ? q8[j] : q8[4 + j]; q4[j] = keep + __shfl_xor(send, 16, 64); }
; #pragma unroll
;   for (int j = 0; j < 2; ++j) { const float keep = b3 ? q4[2 + j] : q4[j], send = b3 ? q4[j] : q4[2 + j]; q2[j] = keep + __shfl_xor(send, 8, 64); }
;   *(unsigned*)(yrow + 16 * (lane & 7) + 2 * (lane >> 3)) = pack2(q2[0], q2[1]);
; DI void phase_ev(const Params& p, const unsigned my_xcc, const unsigned my_rank) {
;     ...
;       EV_IDS(tA2, na0, na1, nca0, nca1);
;       ev_compute(vA, ca0, ca1, ybuf + (size_t)tA * 1024 + 128 * cs, lane);
;       ev_load(vb8, na0, na1, cs, lane, vA);
;       const int tB2 = TOK(k + 3); int nb0, nb1; float ncb0, ncb1;
	v_pk_add_f32 v[6:7], v[6:7], v[8:9]
	v_cndmask_b32_e64 v9, v11, v21, s[6:7]
	v_cndmask_b32_e64 v8, v10, v20, s[6:7]
	v_cndmask_b32_e64 v11, v15, v23, s[6:7]
	v_cndmask_b32_e64 v10, v14, v22, s[6:7]
	v_cndmask_b32_e64 v3, v5, v3, s[6:7]
	v_cndmask_b32_e64 v2, v4, v2, s[6:7]
	s_waitcnt lgkmcnt(4)
	v_pk_add_f32 v[8:9], v[8:9], v[12:13]
	s_waitcnt lgkmcnt(2)
	v_pk_add_f32 v[10:11], v[10:11], v[18:19]
	s_waitcnt lgkmcnt(0)
	v_pk_add_f32 v[2:3], v[2:3], v[24:25]
	v_cndmask_b32_e64 v4, v6, v10, s[8:9]
	v_cndmask_b32_e64 v12, v10, v6, s[8:9]
	v_cndmask_b32_e64 v5, v7, v11, s[8:9]
	v_cndmask_b32_e64 v6, v8, v2, s[8:9]
	v_cndmask_b32_e64 v10, v2, v8, s[8:9]
	v_cndmask_b32_e64 v2, v9, v3, s[8:9]
	ds_bpermute_b32 v4, v178, v4
	v_cndmask_b32_e64 v13, v11, v7, s[8:9]
	ds_bpermute_b32 v5, v178, v5
	ds_bpermute_b32 v6, v178, v6
	ds_bpermute_b32 v7, v178, v2
	v_cndmask_b32_e64 v11, v3, v9, s[8:9]
	ds_bpermute_b32 v164, v168, v183
	s_waitcnt lgkmcnt(3)
	v_pk_add_f32 v[4:5], v[12:13], v[4:5]
	s_waitcnt vmcnt(19)
	v_cvt_pk_f32_fp8_sdwa v[160:161], v127 src0_sel:WORD_1
	s_waitcnt lgkmcnt(1)
	v_pk_add_f32 v[2:3], v[10:11], v[6:7]
	v_cvt_pk_f32_fp8_e32 v[162:163], v128
	v_cndmask_b32_e64 v6, v4, v2, s[10:11]
	v_cndmask_b32_e64 v8, v2, v4, s[10:11]
	v_cndmask_b32_e64 v2, v5, v3, s[10:11]
	ds_bpermute_b32 v6, v179, v6
	ds_bpermute_b32 v7, v179, v2
	v_cndmask_b32_e64 v9, v3, v5, s[10:11]
	v_cvt_pk_f32_fp8_sdwa v[188:189], v128 src0_sel:WORD_1
	v_cvt_pk_f32_fp8_e32 v[190:191], v129
	v_cvt_pk_f32_fp8_sdwa v[192:193], v129 src0_sel:WORD_1
	s_waitcnt lgkmcnt(0)
	v_pk_add_f32 v[2:3], v[8:9], v[6:7]
	s_waitcnt vmcnt(16)
	v_cvt_pk_f32_fp8_e32 v[194:195], v124
	v_cvt_pk_bf16_f32 v4, v2, v3
	v_lshl_add_u64 v[2:3], v[152:153], 0, s[34:35]
	global_store_dword v[2:3], v4, off
	ds_bpermute_b32 v2, v168, v157
	s_add_i32 s34, s0, s38
	s_ashr_i32 s35, s34, 31
	s_lshl_b64 s[0:1], s[34:35], 9
	v_or_b32_e32 v154, s0, v174
	s_waitcnt lgkmcnt(0)
	v_lshl_add_u32 v2, v2, 10, v204
	global_load_dwordx4 v[62:65], v2, s[98:99]
	ds_bpermute_b32 v2, v169, v157
	v_mov_b32_e32 v155, s1
	v_cvt_pk_f32_fp8_sdwa v[196:197], v124 src0_sel:WORD_1
	v_cvt_pk_f32_fp8_e32 v[198:199], v125
	v_cvt_pk_f32_fp8_sdwa v[124:125], v125 src0_sel:WORD_1
	s_waitcnt lgkmcnt(0)
	v_lshl_add_u32 v2, v2, 10, v204
	global_load_dwordx4 v[58:61], v2, s[98:99]
	ds_bpermute_b32 v2, v170, v157
	s_cmp_lt_i32 s24, s40
	s_waitcnt lgkmcnt(0)
	v_lshl_add_u32 v2, v2, 10, v204
	global_load_dwordx4 v[54:57], v2, s[98:99]
	ds_bpermute_b32 v2, v171, v157
	s_waitcnt lgkmcnt(0)
	v_lshl_add_u32 v2, v2, 10, v204
	global_load_dwordx4 v[50:53], v2, s[98:99]
	ds_bpermute_b32 v2, v172, v157
	s_waitcnt lgkmcnt(0)
	v_lshl_add_u32 v2, v2, 10, v204
	global_load_dwordx4 v[46:49], v2, s[98:99]
	ds_bpermute_b32 v2, v173, v157
	s_waitcnt lgkmcnt(0)
	v_lshl_add_u32 v2, v2, 10, v204
	global_load_dwordx4 v[42:45], v2, s[98:99]
	ds_bpermute_b32 v2, v175, v157
	s_waitcnt lgkmcnt(0)
	v_lshl_add_u32 v2, v2, 10, v204
	global_load_dwordx4 v[38:41], v2, s[98:99]
	ds_bpermute_b32 v2, v176, v157
	s_waitcnt lgkmcnt(0)
	v_lshl_add_u32 v2, v2, 10, v204
	global_load_dwordx4 v[34:37], v2, s[98:99]
	s_waitcnt vmcnt(22)
	ds_bpermute_b32 v2, v168, v156
	s_waitcnt lgkmcnt(0)
	v_lshl_add_u32 v2, v2, 10, v204
	global_load_dwordx4 v[30:33], v2, s[98:99]
	ds_bpermute_b32 v2, v169, v156
	s_waitcnt lgkmcnt(0)
	v_lshl_add_u32 v2, v2, 10, v204
	global_load_dwordx4 v[26:29], v2, s[98:99]
	ds_bpermute_b32 v2, v170, v156
	s_waitcnt lgkmcnt(0)
	v_lshl_add_u32 v2, v2, 10, v204
	global_load_dwordx4 v[22:25], v2, s[98:99]
	ds_bpermute_b32 v2, v171, v156
	s_waitcnt lgkmcnt(0)
	v_lshl_add_u32 v2, v2, 10, v204
	global_load_dwordx4 v[18:21], v2, s[98:99]
	ds_bpermute_b32 v2, v172, v156
	s_waitcnt lgkmcnt(0)
	v_lshl_add_u32 v2, v2, 10, v204
	global_load_dwordx4 v[14:17], v2, s[98:99]
	ds_bpermute_b32 v2, v173, v156
	s_waitcnt lgkmcnt(0)
	v_lshl_add_u32 v2, v2, 10, v204
	global_load_dwordx4 v[10:13], v2, s[98:99]
	ds_bpermute_b32 v2, v175, v156
	s_waitcnt lgkmcnt(0)
	v_lshl_add_u32 v2, v2, 10, v204
	global_load_dwordx4 v[6:9], v2, s[98:99]
	ds_bpermute_b32 v2, v176, v156
	v_lshl_add_u64 v[156:157], s[26:27], 0, v[154:155]
	global_load_dword v185, v[156:157], off
	v_or_b32_e32 v156, 0x100, v154
	v_mov_b32_e32 v157, s1
	s_waitcnt lgkmcnt(0)
	v_lshl_add_u32 v2, v2, 10, v204
	v_lshl_add_u64 v[158:159], s[26:27], 0, v[156:157]
	v_lshl_add_u64 v[154:155], s[28:29], 0, v[154:155]
	global_load_dwordx4 v[2:5], v2, s[98:99]
	s_nop 0
	global_load_dword v184, v[158:159], off
	global_load_dword v186, v[154:155], off
	v_lshl_add_u64 v[154:155], s[28:29], 0, v[156:157]
	global_load_dword v187, v[154:155], off
	v_cvt_pk_f32_fp8_e32 v[154:155], v126
	v_cvt_pk_f32_fp8_sdwa v[156:157], v126 src0_sel:WORD_1
	v_cvt_pk_f32_fp8_e32 v[158:159], v127
	v_pk_fma_f32 v[126:127], v[154:155], v[164:165], 0 op_sel_hi:[1,0,0]
	v_pk_fma_f32 v[128:129], v[156:157], v[164:165], 0 op_sel_hi:[1,0,0]
	v_pk_fma_f32 v[154:155], v[158:159], v[164:165], 0 op_sel_hi:[1,0,0]
	v_pk_fma_f32 v[156:157], v[160:161], v[164:165], 0 op_sel_hi:[1,0,0]
	v_pk_fma_f32 v[158:159], v[162:163], v[164:165], 0 op_sel_hi:[1,0,0]
	v_pk_fma_f32 v[160:161], v[188:189], v[164:165], 0 op_sel_hi:[1,0,0]
	v_pk_fma_f32 v[162:163], v[190:191], v[164:165], 0 op_sel_hi:[1,0,0]
	v_pk_fma_f32 v[164:165], v[192:193], v[164:165], 0 op_sel_hi:[1,0,0]
	v_cvt_pk_f32_fp8_e32 v[188:189], v122
	v_cvt_pk_f32_fp8_sdwa v[190:191], v122 src0_sel:WORD_1
	v_cvt_pk_f32_fp8_e32 v[192:193], v123
	v_cvt_pk_f32_fp8_sdwa v[122:123], v123 src0_sel:WORD_1
	v_pk_fma_f32 v[126:127], v[188:189], v[166:167], v[126:127] op_sel_hi:[1,0,1]
	v_pk_fma_f32 v[128:129], v[190:191], v[166:167], v[128:129] op_sel_hi:[1,0,1]
	v_pk_fma_f32 v[154:155], v[192:193], v[166:167], v[154:155] op_sel_hi:[1,0,1]
	v_pk_fma_f32 v[122:123], v[122:123], v[166:167], v[156:157] op_sel_hi:[1,0,1]
	v_pk_fma_f32 v[156:157], v[194:195], v[166:167], v[158:159] op_sel_hi:[1,0,1]
	v_pk_fma_f32 v[158:159], v[196:197], v[166:167], v[160:161] op_sel_hi:[1,0,1]
	v_pk_fma_f32 v[160:161], v[198:199], v[166:167], v[162:163] op_sel_hi:[1,0,1]
	ds_bpermute_b32 v162, v170, v183
	v_cvt_pk_f32_fp8_e32 v[192:193], v120
	v_cvt_pk_f32_fp8_sdwa v[194:195], v120 src0_sel:WORD_1
	v_cvt_pk_f32_fp8_e32 v[196:197], v121
	v_cvt_pk_f32_fp8_sdwa v[120:121], v121 src0_sel:WORD_1
	v_pk_fma_f32 v[124:125], v[124:125], v[166:167], v[164:165] op_sel_hi:[1,0,1]
	v_cvt_pk_f32_fp8_e32 v[164:165], v118
	v_cvt_pk_f32_fp8_sdwa v[188:189], v118 src0_sel:WORD_1
	v_cvt_pk_f32_fp8_e32 v[190:191], v119
	v_cvt_pk_f32_fp8_sdwa v[118:119], v119 src0_sel:WORD_1
	s_waitcnt lgkmcnt(0)
; DI void ev_compute(const uint4 (&v)[16], const float c0, const float c1, u16* __restrict__ yrow, const int lane) {
;   f32x2 acc[8];
; #pragma unroll
;   for (int k = 0; k < 8; ++k) acc[k] = f32x2{0.f, 0.f};
; #pragma unroll
;   for (int i = 0; i < 16; ++i) {
;     const float c = __shfl(i < 8 ? c0 : c1, (8 * i + (lane >> 3)) & 63, 64);
;     const f32x2 cc = f32x2{c, c};
;     f32x2 vf[8];
;     fp8x16_to_f32(v[i], vf);
; #pragma unroll
;     for (int k = 0; k < 8; ++k) acc[k] = __builtin_elementwise_fma(vf[k], cc, acc[k]);
;   }
	v_pk_fma_f32 v[120:121], v[120:121], v[162:163], v[124:125] op_sel_hi:[1,0,1]
	ds_bpermute_b32 v124, v171, v183
	v_pk_fma_f32 v[128:129], v[188:189], v[162:163], v[128:129] op_sel_hi:[1,0,1]
	v_pk_fma_f32 v[154:155], v[190:191], v[162:163], v[154:155] op_sel_hi:[1,0,1]
	v_pk_fma_f32 v[118:119], v[118:119], v[162:163], v[122:123] op_sel_hi:[1,0,1]
	v_pk_fma_f32 v[122:123], v[192:193], v[162:163], v[156:157] op_sel_hi:[1,0,1]
	s_waitcnt vmcnt(33)
	v_cvt_pk_f32_fp8_e32 v[188:189], v116
	v_cvt_pk_f32_fp8_sdwa v[190:191], v116 src0_sel:WORD_1
	v_cvt_pk_f32_fp8_e32 v[192:193], v117
	v_cvt_pk_f32_fp8_sdwa v[116:117], v117 src0_sel:WORD_1
	v_pk_fma_f32 v[126:127], v[164:165], v[162:163], v[126:127] op_sel_hi:[1,0,1]
	v_pk_fma_f32 v[156:157], v[194:195], v[162:163], v[158:159] op_sel_hi:[1,0,1]
	v_pk_fma_f32 v[158:159], v[196:197], v[162:163], v[160:161] op_sel_hi:[1,0,1]
	v_cvt_pk_f32_fp8_e32 v[160:161], v114
	v_cvt_pk_f32_fp8_sdwa v[162:163], v114 src0_sel:WORD_1
	v_cvt_pk_f32_fp8_e32 v[164:165], v115
	v_cvt_pk_f32_fp8_sdwa v[114:115], v115 src0_sel:WORD_1
	s_waitcnt lgkmcnt(0)
	v_pk_fma_f32 v[116:117], v[116:117], v[124:125], v[120:121] op_sel_hi:[1,0,1]
	ds_bpermute_b32 v120, v172, v183
	v_pk_fma_f32 v[128:129], v[162:163], v[124:125], v[128:129] op_sel_hi:[1,0,1]
	v_pk_fma_f32 v[154:155], v[164:165], v[124:125], v[154:155] op_sel_hi:[1,0,1]
	v_pk_fma_f32 v[114:115], v[114:115], v[124:125], v[118:119] op_sel_hi:[1,0,1]
	v_pk_fma_f32 v[118:119], v[188:189], v[124:125], v[122:123] op_sel_hi:[1,0,1]
	s_waitcnt vmcnt(32)
	v_cvt_pk_f32_fp8_e32 v[162:163], v112
	v_cvt_pk_f32_fp8_sdwa v[164:165], v112 src0_sel:WORD_1
	v_cvt_pk_f32_fp8_e32 v[188:189], v113
	v_cvt_pk_f32_fp8_sdwa v[112:113], v113 src0_sel:WORD_1
	v_pk_fma_f32 v[126:127], v[160:161], v[124:125], v[126:127] op_sel_hi:[1,0,1]
	v_pk_fma_f32 v[122:123], v[190:191], v[124:125], v[156:157] op_sel_hi:[1,0,1]
	v_pk_fma_f32 v[156:157], v[192:193], v[124:125], v[158:159] op_sel_hi:[1,0,1]
	v_cvt_pk_f32_fp8_e32 v[124:125], v110
	v_cvt_pk_f32_fp8_sdwa v[158:159], v110 src0_sel:WORD_1
	v_cvt_pk_f32_fp8_e32 v[160:161], v111
	v_cvt_pk_f32_fp8_sdwa v[110:111], v111 src0_sel:WORD_1
	s_waitcnt lgkmcnt(0)
	v_pk_fma_f32 v[112:113], v[112:113], v[120:121], v[116:117] op_sel_hi:[1,0,1]
	ds_bpermute_b32 v116, v173, v183
	v_pk_fma_f32 v[124:125], v[124:125], v[120:121], v[126:127] op_sel_hi:[1,0,1]
	v_pk_fma_f32 v[126:127], v[158:159], v[120:121], v[128:129] op_sel_hi:[1,0,1]
	v_pk_fma_f32 v[128:129], v[160:161], v[120:121], v[154:155] op_sel_hi:[1,0,1]
	v_pk_fma_f32 v[110:111], v[110:111], v[120:121], v[114:115] op_sel_hi:[1,0,1]
	v_pk_fma_f32 v[114:115], v[162:163], v[120:121], v[118:119] op_sel_hi:[1,0,1]
	s_waitcnt vmcnt(31)
	v_cvt_pk_f32_fp8_e32 v[158:159], v108
	v_cvt_pk_f32_fp8_sdwa v[160:161], v108 src0_sel:WORD_1
	v_cvt_pk_f32_fp8_e32 v[162:163], v109
	v_cvt_pk_f32_fp8_sdwa v[108:109], v109 src0_sel:WORD_1
	v_pk_fma_f32 v[118:119], v[164:165], v[120:121], v[122:123] op_sel_hi:[1,0,1]
	v_pk_fma_f32 v[122:123], v[188:189], v[120:121], v[156:157] op_sel_hi:[1,0,1]
	v_cvt_pk_f32_fp8_e32 v[120:121], v106
	v_cvt_pk_f32_fp8_sdwa v[154:155], v106 src0_sel:WORD_1
	v_cvt_pk_f32_fp8_e32 v[156:157], v107
	v_cvt_pk_f32_fp8_sdwa v[106:107], v107 src0_sel:WORD_1
	s_waitcnt lgkmcnt(0)
	v_pk_fma_f32 v[108:109], v[108:109], v[116:117], v[112:113] op_sel_hi:[1,0,1]
	ds_bpermute_b32 v112, v175, v183
	v_pk_fma_f32 v[120:121], v[120:121], v[116:117], v[124:125] op_sel_hi:[1,0,1]
	v_pk_fma_f32 v[124:125], v[154:155], v[116:117], v[126:127] op_sel_hi:[1,0,1]
	v_pk_fma_f32 v[126:127], v[156:157], v[116:117], v[128:129] op_sel_hi:[1,0,1]
	v_pk_fma_f32 v[106:107], v[106:107], v[116:117], v[110:111] op_sel_hi:[1,0,1]
	v_pk_fma_f32 v[110:111], v[158:159], v[116:117], v[114:115] op_sel_hi:[1,0,1]
	s_waitcnt vmcnt(30)
	v_cvt_pk_f32_fp8_e32 v[154:155], v104
	v_cvt_pk_f32_fp8_sdwa v[156:157], v104 src0_sel:WORD_1
	v_cvt_pk_f32_fp8_e32 v[158:159], v105
	v_cvt_pk_f32_fp8_sdwa v[104:105], v105 src0_sel:WORD_1
	v_pk_fma_f32 v[114:115], v[160:161], v[116:117], v[118:119] op_sel_hi:[1,0,1]
	v_pk_fma_f32 v[118:119], v[162:163], v[116:117], v[122:123] op_sel_hi:[1,0,1]
	v_cvt_pk_f32_fp8_e32 v[116:117], v102
	v_cvt_pk_f32_fp8_sdwa v[122:123], v102 src0_sel:WORD_1
	v_cvt_pk_f32_fp8_e32 v[128:129], v103
	v_cvt_pk_f32_fp8_sdwa v[102:103], v103 src0_sel:WORD_1
	s_waitcnt lgkmcnt(0)
	v_pk_fma_f32 v[104:105], v[104:105], v[112:113], v[108:109] op_sel_hi:[1,0,1]
	ds_bpermute_b32 v108, v176, v183
	v_pk_fma_f32 v[116:117], v[116:117], v[112:113], v[120:121] op_sel_hi:[1,0,1]
	v_pk_fma_f32 v[120:121], v[122:123], v[112:113], v[124:125] op_sel_hi:[1,0,1]
	v_pk_fma_f32 v[122:123], v[128:129], v[112:113], v[126:127] op_sel_hi:[1,0,1]
	v_pk_fma_f32 v[102:103], v[102:103], v[112:113], v[106:107] op_sel_hi:[1,0,1]
	v_pk_fma_f32 v[106:107], v[154:155], v[112:113], v[110:111] op_sel_hi:[1,0,1]
	s_waitcnt vmcnt(29)
	v_cvt_pk_f32_fp8_e32 v[126:127], v100
	v_cvt_pk_f32_fp8_sdwa v[128:129], v100 src0_sel:WORD_1
	v_cvt_pk_f32_fp8_e32 v[154:155], v101
	v_cvt_pk_f32_fp8_sdwa v[100:101], v101 src0_sel:WORD_1
	v_pk_fma_f32 v[110:111], v[156:157], v[112:113], v[114:115] op_sel_hi:[1,0,1]
	v_pk_fma_f32 v[114:115], v[158:159], v[112:113], v[118:119] op_sel_hi:[1,0,1]
	v_cvt_pk_f32_fp8_e32 v[112:113], v98
	v_cvt_pk_f32_fp8_sdwa v[118:119], v98 src0_sel:WORD_1
	v_cvt_pk_f32_fp8_e32 v[124:125], v99
	v_cvt_pk_f32_fp8_sdwa v[98:99], v99 src0_sel:WORD_1
	s_waitcnt lgkmcnt(0)
; DI void ev_compute(const uint4 (&v)[16], const float c0, const float c1, u16* __restrict__ yrow, const int lane) {
;   f32x2 acc[8];
; #pragma unroll
;   for (int k = 0; k < 8; ++k) acc[k] = f32x2{0.f, 0.f};
; #pragma unroll
;   for (int i = 0; i < 16; ++i) {
;     const float c = __shfl(i < 8 ? c0 : c1, (8 * i + (lane >> 3)) & 63, 64);
;     const f32x2 cc = f32x2{c, c};
;     f32x2 vf[8];
;     fp8x16_to_f32(v[i], vf);
; #pragma unroll
;     for (int k = 0; k < 8; ++k) acc[k] = __builtin_elementwise_fma(vf[k], cc, acc[k]);
;   }
	v_pk_fma_f32 v[100:101], v[100:101], v[108:109], v[104:105] op_sel_hi:[1,0,1]
	ds_bpermute_b32 v104, v168, v180
	v_pk_fma_f32 v[112:113], v[112:113], v[108:109], v[116:117] op_sel_hi:[1,0,1]
	v_pk_fma_f32 v[116:117], v[118:119], v[108:109], v[120:121] op_sel_hi:[1,0,1]
	v_pk_fma_f32 v[118:119], v[124:125], v[108:109], v[122:123] op_sel_hi:[1,0,1]
	v_pk_fma_f32 v[98:99], v[98:99], v[108:109], v[102:103] op_sel_hi:[1,0,1]
	v_pk_fma_f32 v[102:103], v[126:127], v[108:109], v[106:107] op_sel_hi:[1,0,1]
	s_waitcnt vmcnt(28)
	v_cvt_pk_f32_fp8_e32 v[122:123], v96
	v_cvt_pk_f32_fp8_sdwa v[124:125], v96 src0_sel:WORD_1
	v_cvt_pk_f32_fp8_e32 v[126:127], v97
	v_cvt_pk_f32_fp8_sdwa v[96:97], v97 src0_sel:WORD_1
	v_pk_fma_f32 v[106:107], v[128:129], v[108:109], v[110:111] op_sel_hi:[1,0,1]
	v_pk_fma_f32 v[110:111], v[154:155], v[108:109], v[114:115] op_sel_hi:[1,0,1]
	v_cvt_pk_f32_fp8_e32 v[108:109], v94
	v_cvt_pk_f32_fp8_sdwa v[114:115], v94 src0_sel:WORD_1
	v_cvt_pk_f32_fp8_e32 v[120:121], v95
	v_cvt_pk_f32_fp8_sdwa v[94:95], v95 src0_sel:WORD_1
	s_waitcnt lgkmcnt(0)
	v_pk_fma_f32 v[96:97], v[96:97], v[104:105], v[100:101] op_sel_hi:[1,0,1]
	ds_bpermute_b32 v100, v169, v180
	v_pk_fma_f32 v[108:109], v[108:109], v[104:105], v[112:113] op_sel_hi:[1,0,1]
	v_pk_fma_f32 v[112:113], v[114:115], v[104:105], v[116:117] op_sel_hi:[1,0,1]
	v_pk_fma_f32 v[114:115], v[120:121], v[104:105], v[118:119] op_sel_hi:[1,0,1]
	v_pk_fma_f32 v[94:95], v[94:95], v[104:105], v[98:99] op_sel_hi:[1,0,1]
	v_pk_fma_f32 v[98:99], v[122:123], v[104:105], v[102:103] op_sel_hi:[1,0,1]
	s_waitcnt vmcnt(27)
	v_cvt_pk_f32_fp8_e32 v[118:119], v92
	v_cvt_pk_f32_fp8_sdwa v[120:121], v92 src0_sel:WORD_1
	v_cvt_pk_f32_fp8_e32 v[122:123], v93
	v_cvt_pk_f32_fp8_sdwa v[92:93], v93 src0_sel:WORD_1
	v_pk_fma_f32 v[102:103], v[124:125], v[104:105], v[106:107] op_sel_hi:[1,0,1]
	v_pk_fma_f32 v[106:107], v[126:127], v[104:105], v[110:111] op_sel_hi:[1,0,1]
	v_cvt_pk_f32_fp8_e32 v[104:105], v90
	v_cvt_pk_f32_fp8_sdwa v[110:111], v90 src0_sel:WORD_1
	v_cvt_pk_f32_fp8_e32 v[116:117], v91
	v_cvt_pk_f32_fp8_sdwa v[90:91], v91 src0_sel:WORD_1
	s_waitcnt lgkmcnt(0)
	v_pk_fma_f32 v[92:93], v[92:93], v[100:101], v[96:97] op_sel_hi:[1,0,1]
	ds_bpermute_b32 v96, v170, v180
	v_pk_fma_f32 v[104:105], v[104:105], v[100:101], v[108:109] op_sel_hi:[1,0,1]
	v_pk_fma_f32 v[108:109], v[110:111], v[100:101], v[112:113] op_sel_hi:[1,0,1]
	v_pk_fma_f32 v[110:111], v[116:117], v[100:101], v[114:115] op_sel_hi:[1,0,1]
	v_pk_fma_f32 v[90:91], v[90:91], v[100:101], v[94:95] op_sel_hi:[1,0,1]
	v_pk_fma_f32 v[94:95], v[118:119], v[100:101], v[98:99] op_sel_hi:[1,0,1]
	s_waitcnt vmcnt(26)
	v_cvt_pk_f32_fp8_e32 v[114:115], v88
	v_cvt_pk_f32_fp8_sdwa v[116:117], v88 src0_sel:WORD_1
	v_cvt_pk_f32_fp8_e32 v[118:119], v89
	v_cvt_pk_f32_fp8_sdwa v[88:89], v89 src0_sel:WORD_1
	v_pk_fma_f32 v[98:99], v[120:121], v[100:101], v[102:103] op_sel_hi:[1,0,1]
	v_pk_fma_f32 v[102:103], v[122:123], v[100:101], v[106:107] op_sel_hi:[1,0,1]
	v_cvt_pk_f32_fp8_e32 v[100:101], v86
	v_cvt_pk_f32_fp8_sdwa v[106:107], v86 src0_sel:WORD_1
	v_cvt_pk_f32_fp8_e32 v[112:113], v87
	v_cvt_pk_f32_fp8_sdwa v[86:87], v87 src0_sel:WORD_1
	s_waitcnt lgkmcnt(0)
	v_pk_fma_f32 v[88:89], v[88:89], v[96:97], v[92:93] op_sel_hi:[1,0,1]
	ds_bpermute_b32 v92, v171, v180
	v_pk_fma_f32 v[100:101], v[100:101], v[96:97], v[104:105] op_sel_hi:[1,0,1]
	v_pk_fma_f32 v[104:105], v[106:107], v[96:97], v[108:109] op_sel_hi:[1,0,1]
	v_pk_fma_f32 v[106:107], v[112:113], v[96:97], v[110:111] op_sel_hi:[1,0,1]
	v_pk_fma_f32 v[86:87], v[86:87], v[96:97], v[90:91] op_sel_hi:[1,0,1]
	v_pk_fma_f32 v[90:91], v[114:115], v[96:97], v[94:95] op_sel_hi:[1,0,1]
	s_waitcnt vmcnt(25)
	v_cvt_pk_f32_fp8_e32 v[110:111], v84
	v_cvt_pk_f32_fp8_sdwa v[112:113], v84 src0_sel:WORD_1
	v_cvt_pk_f32_fp8_e32 v[114:115], v85
	v_cvt_pk_f32_fp8_sdwa v[84:85], v85 src0_sel:WORD_1
	v_pk_fma_f32 v[94:95], v[116:117], v[96:97], v[98:99] op_sel_hi:[1,0,1]
	v_pk_fma_f32 v[98:99], v[118:119], v[96:97], v[102:103] op_sel_hi:[1,0,1]
	v_cvt_pk_f32_fp8_e32 v[96:97], v82
	v_cvt_pk_f32_fp8_sdwa v[102:103], v82 src0_sel:WORD_1
	v_cvt_pk_f32_fp8_e32 v[108:109], v83
	v_cvt_pk_f32_fp8_sdwa v[82:83], v83 src0_sel:WORD_1
	s_waitcnt lgkmcnt(0)
	v_pk_fma_f32 v[84:85], v[84:85], v[92:93], v[88:89] op_sel_hi:[1,0,1]
	ds_bpermute_b32 v88, v172, v180
	v_pk_fma_f32 v[96:97], v[96:97], v[92:93], v[100:101] op_sel_hi:[1,0,1]
	v_pk_fma_f32 v[100:101], v[102:103], v[92:93], v[104:105] op_sel_hi:[1,0,1]
	v_pk_fma_f32 v[102:103], v[108:109], v[92:93], v[106:107] op_sel_hi:[1,0,1]
	v_pk_fma_f32 v[82:83], v[82:83], v[92:93], v[86:87] op_sel_hi:[1,0,1]
	v_pk_fma_f32 v[86:87], v[110:111], v[92:93], v[90:91] op_sel_hi:[1,0,1]
	s_waitcnt vmcnt(24)
	v_cvt_pk_f32_fp8_e32 v[106:107], v80
	v_cvt_pk_f32_fp8_sdwa v[108:109], v80 src0_sel:WORD_1
	v_cvt_pk_f32_fp8_e32 v[110:111], v81
	v_cvt_pk_f32_fp8_sdwa v[80:81], v81 src0_sel:WORD_1
	v_pk_fma_f32 v[90:91], v[112:113], v[92:93], v[94:95] op_sel_hi:[1,0,1]
	v_pk_fma_f32 v[94:95], v[114:115], v[92:93], v[98:99] op_sel_hi:[1,0,1]
	v_cvt_pk_f32_fp8_e32 v[92:93], v78
	v_cvt_pk_f32_fp8_sdwa v[98:99], v78 src0_sel:WORD_1
	v_cvt_pk_f32_fp8_e32 v[104:105], v79
	v_cvt_pk_f32_fp8_sdwa v[78:79], v79 src0_sel:WORD_1
	s_waitcnt lgkmcnt(0)
	v_pk_fma_f32 v[80:81], v[80:81], v[88:89], v[84:85] op_sel_hi:[1,0,1]
	ds_bpermute_b32 v84, v173, v180
	v_pk_fma_f32 v[92:93], v[92:93], v[88:89], v[96:97] op_sel_hi:[1,0,1]
	v_pk_fma_f32 v[96:97], v[98:99], v[88:89], v[100:101] op_sel_hi:[1,0,1]
	v_pk_fma_f32 v[98:99], v[104:105], v[88:89], v[102:103] op_sel_hi:[1,0,1]
	v_pk_fma_f32 v[78:79], v[78:79], v[88:89], v[82:83] op_sel_hi:[1,0,1]
	v_pk_fma_f32 v[82:83], v[106:107], v[88:89], v[86:87] op_sel_hi:[1,0,1]
	s_waitcnt vmcnt(23)
; DI unsigned pack2(float a, float b) { const f32x2 v = {a, b}; const bf16x2_t r = __builtin_convertvector(v, bf16x2_t); return __builtin_bit_cast(unsigned, r); }
; DI void ev_compute(const uint4 (&v)[16], const float c0, const float c1, u16* __restrict__ yrow, const int lane) {
;     ...
;   float a[16];
; #pragma unroll
;   for (int k = 0; k < 8; ++k) { a[2 * k] = acc[k][0]; a[2 * k + 1] = acc[k][1]; }
;   float q8[8], q4[4], q2[2];
;   const bool b5 = lane & 32, b4 = lane & 16, b3 = lane & 8;
; #pragma unroll
;   for (int j = 0; j < 8; ++j) { const float keep = b5 ? a[8 + j] : a[j], send = b5 ? a[j] : a[8 + j]; q8[j] = keep + __shfl_xor(send, 32, 64); }
; #pragma unroll
;   for (int j = 0; j < 4; ++j) { const float keep = b4 ? q8[4 + j] : q8[j], send = b4 ? q8[j] : q8[4 + j]; q4[j] = keep + __shfl_xor(send, 16, 64); }
; #pragma unroll
;   for (int j = 0; j < 2; ++j) { const float keep = b3 ? q4[2 + j] : q4[j], send = b3 ? q4[j] : q4[2 + j]; q2[j] = keep + __shfl_xor(send, 8, 64); }
;   *(unsigned*)(yrow + 16 * (lane & 7) + 2 * (lane >> 3)) = pack2(q2[0], q2[1]);
; DI void phase_ev(const Params& p, const unsigned my_xcc, const unsigned my_rank) {
;     ...
;       ev_compute(vB, cb0, cb1, ybuf + (size_t)tB * 1024 + 128 * cs, lane);
;       tA = tA2; a0 = na0; a1 = na1; ca0 = nca0; ca1 = nca1; tB = tB2; b0 = nb0; b1 = nb1; cb0 = ncb0; cb1 = ncb1;
	v_cvt_pk_f32_fp8_e32 v[102:103], v76
	v_cvt_pk_f32_fp8_sdwa v[104:105], v76 src0_sel:WORD_1
	v_cvt_pk_f32_fp8_e32 v[106:107], v77
	v_cvt_pk_f32_fp8_sdwa v[76:77], v77 src0_sel:WORD_1
	v_pk_fma_f32 v[86:87], v[108:109], v[88:89], v[90:91] op_sel_hi:[1,0,1]
	v_pk_fma_f32 v[90:91], v[110:111], v[88:89], v[94:95] op_sel_hi:[1,0,1]
	v_cvt_pk_f32_fp8_e32 v[88:89], v74
	v_cvt_pk_f32_fp8_sdwa v[94:95], v74 src0_sel:WORD_1
	v_cvt_pk_f32_fp8_e32 v[100:101], v75
	v_cvt_pk_f32_fp8_sdwa v[74:75], v75 src0_sel:WORD_1
	s_waitcnt lgkmcnt(0)
	v_pk_fma_f32 v[76:77], v[76:77], v[84:85], v[80:81] op_sel_hi:[1,0,1]
	ds_bpermute_b32 v80, v175, v180
	v_pk_fma_f32 v[88:89], v[88:89], v[84:85], v[92:93] op_sel_hi:[1,0,1]
	v_pk_fma_f32 v[92:93], v[94:95], v[84:85], v[96:97] op_sel_hi:[1,0,1]
	v_pk_fma_f32 v[94:95], v[100:101], v[84:85], v[98:99] op_sel_hi:[1,0,1]
	v_pk_fma_f32 v[74:75], v[74:75], v[84:85], v[78:79] op_sel_hi:[1,0,1]
	v_pk_fma_f32 v[78:79], v[102:103], v[84:85], v[82:83] op_sel_hi:[1,0,1]
	s_waitcnt vmcnt(22)
	v_cvt_pk_f32_fp8_e32 v[98:99], v72
	v_cvt_pk_f32_fp8_sdwa v[100:101], v72 src0_sel:WORD_1
	v_cvt_pk_f32_fp8_e32 v[102:103], v73
	v_cvt_pk_f32_fp8_sdwa v[72:73], v73 src0_sel:WORD_1
	v_pk_fma_f32 v[82:83], v[104:105], v[84:85], v[86:87] op_sel_hi:[1,0,1]
	v_pk_fma_f32 v[86:87], v[106:107], v[84:85], v[90:91] op_sel_hi:[1,0,1]
	v_cvt_pk_f32_fp8_e32 v[84:85], v70
	v_cvt_pk_f32_fp8_sdwa v[90:91], v70 src0_sel:WORD_1
	v_cvt_pk_f32_fp8_e32 v[96:97], v71
	v_cvt_pk_f32_fp8_sdwa v[70:71], v71 src0_sel:WORD_1
	s_waitcnt lgkmcnt(0)
	v_pk_fma_f32 v[72:73], v[72:73], v[80:81], v[76:77] op_sel_hi:[1,0,1]
	ds_bpermute_b32 v76, v176, v180
	v_pk_fma_f32 v[84:85], v[84:85], v[80:81], v[88:89] op_sel_hi:[1,0,1]
	v_pk_fma_f32 v[88:89], v[90:91], v[80:81], v[92:93] op_sel_hi:[1,0,1]
	v_pk_fma_f32 v[90:91], v[96:97], v[80:81], v[94:95] op_sel_hi:[1,0,1]
	v_pk_fma_f32 v[70:71], v[70:71], v[80:81], v[74:75] op_sel_hi:[1,0,1]
	v_pk_fma_f32 v[74:75], v[98:99], v[80:81], v[78:79] op_sel_hi:[1,0,1]
	v_pk_fma_f32 v[78:79], v[100:101], v[80:81], v[82:83] op_sel_hi:[1,0,1]
	v_pk_fma_f32 v[82:83], v[102:103], v[80:81], v[86:87] op_sel_hi:[1,0,1]
	s_waitcnt vmcnt(21)
	v_cvt_pk_f32_fp8_e32 v[80:81], v66
	v_cvt_pk_f32_fp8_sdwa v[86:87], v66 src0_sel:WORD_1
	v_cvt_pk_f32_fp8_e32 v[92:93], v67
	v_cvt_pk_f32_fp8_sdwa v[66:67], v67 src0_sel:WORD_1
	v_cvt_pk_f32_fp8_e32 v[94:95], v68
	v_cvt_pk_f32_fp8_sdwa v[96:97], v68 src0_sel:WORD_1
	v_cvt_pk_f32_fp8_e32 v[98:99], v69
	v_cvt_pk_f32_fp8_sdwa v[68:69], v69 src0_sel:WORD_1
	s_waitcnt lgkmcnt(0)
	v_pk_fma_f32 v[80:81], v[80:81], v[76:77], v[84:85] op_sel_hi:[1,0,1]
	v_pk_fma_f32 v[66:67], v[66:67], v[76:77], v[70:71] op_sel_hi:[1,0,1]
	v_pk_fma_f32 v[70:71], v[94:95], v[76:77], v[74:75] op_sel_hi:[1,0,1]
	v_pk_fma_f32 v[84:85], v[86:87], v[76:77], v[88:89] op_sel_hi:[1,0,1]
	v_pk_fma_f32 v[86:87], v[92:93], v[76:77], v[90:91] op_sel_hi:[1,0,1]
	v_pk_fma_f32 v[74:75], v[96:97], v[76:77], v[78:79] op_sel_hi:[1,0,1]
	v_pk_fma_f32 v[78:79], v[98:99], v[76:77], v[82:83] op_sel_hi:[1,0,1]
	v_pk_fma_f32 v[68:69], v[68:69], v[76:77], v[72:73] op_sel_hi:[1,0,1]
	v_cndmask_b32_e64 v72, v80, v70, s[6:7]
	v_cndmask_b32_e64 v73, v81, v71, s[6:7]
	ds_bpermute_b32 v72, v177, v72
	ds_bpermute_b32 v73, v177, v73
	v_cndmask_b32_e64 v76, v84, v74, s[6:7]
	v_cndmask_b32_e64 v77, v85, v75, s[6:7]
	v_cndmask_b32_e64 v82, v86, v78, s[6:7]
	v_cndmask_b32_e64 v83, v87, v79, s[6:7]
	v_cndmask_b32_e64 v88, v66, v68, s[6:7]
	v_cndmask_b32_e64 v89, v67, v69, s[6:7]
	ds_bpermute_b32 v76, v177, v76
	ds_bpermute_b32 v77, v177, v77
	ds_bpermute_b32 v82, v177, v82
	ds_bpermute_b32 v83, v177, v83
	ds_bpermute_b32 v88, v177, v88
	ds_bpermute_b32 v89, v177, v89
	v_cndmask_b32_e64 v71, v71, v81, s[6:7]
	v_cndmask_b32_e64 v70, v70, v80, s[6:7]
	s_waitcnt lgkmcnt(6)
	v_pk_add_f32 v[70:71], v[70:71], v[72:73]
	v_cndmask_b32_e64 v73, v75, v85, s[6:7]
	v_cndmask_b32_e64 v72, v74, v84, s[6:7]
	v_cndmask_b32_e64 v75, v79, v87, s[6:7]
	v_cndmask_b32_e64 v74, v78, v86, s[6:7]
	v_cndmask_b32_e64 v67, v69, v67, s[6:7]
	v_cndmask_b32_e64 v66, v68, v66, s[6:7]
	s_waitcnt lgkmcnt(4)
	v_pk_add_f32 v[72:73], v[72:73], v[76:77]
	s_waitcnt lgkmcnt(2)
	v_pk_add_f32 v[74:75], v[74:75], v[82:83]
	s_waitcnt lgkmcnt(0)
	v_pk_add_f32 v[66:67], v[66:67], v[88:89]
	v_cndmask_b32_e64 v68, v70, v74, s[8:9]
	v_cndmask_b32_e64 v76, v74, v70, s[8:9]
	v_cndmask_b32_e64 v69, v71, v75, s[8:9]
	v_cndmask_b32_e64 v70, v72, v66, s[8:9]
	v_cndmask_b32_e64 v74, v66, v72, s[8:9]
	v_cndmask_b32_e64 v66, v73, v67, s[8:9]
	ds_bpermute_b32 v68, v178, v68
	v_cndmask_b32_e64 v77, v75, v71, s[8:9]
	ds_bpermute_b32 v69, v178, v69
	ds_bpermute_b32 v70, v178, v70
	ds_bpermute_b32 v71, v178, v66
	v_cndmask_b32_e64 v75, v67, v73, s[8:9]
	v_mov_b32_e32 v155, v181
	s_waitcnt lgkmcnt(2)
	v_pk_add_f32 v[68:69], v[76:77], v[68:69]
	v_mov_b32_e32 v154, v182
	s_waitcnt lgkmcnt(0)
	v_pk_add_f32 v[66:67], v[74:75], v[70:71]
	s_waitcnt vmcnt(0)
	v_mov_b32_e32 v180, v187
	v_cndmask_b32_e64 v70, v68, v66, s[10:11]
	v_cndmask_b32_e64 v72, v66, v68, s[10:11]
	v_cndmask_b32_e64 v66, v69, v67, s[10:11]
	ds_bpermute_b32 v70, v179, v70
	ds_bpermute_b32 v71, v179, v66
	v_cndmask_b32_e64 v73, v67, v69, s[10:11]
	v_mov_b32_e32 v183, v186
	s_waitcnt lgkmcnt(0)
	v_pk_add_f32 v[66:67], v[72:73], v[70:71]
	s_nop 0
	v_cvt_pk_bf16_f32 v68, v66, v67
	v_lshl_add_u64 v[66:67], v[152:153], 0, s[30:31]
	s_mov_b32 s30, s34
	global_store_dword v[66:67], v68, off
	s_cbranch_scc1 .LBB0_570
	s_branch .LBB0_566
